# DPP for intra-wave movement: xor-1/2/4/8 steps of the wave_sum butterflies (conv LayerNorm, SGU stats, prologue row pass) as v_add_f32_dpp instead of ds_bpermute round trips
# speedup vs baseline: 1.0111x; 1.0111x over previous
; __device__ __forceinline__ float bflo(unsigned u) { return __uint_as_float(u << 16); }
; __device__ __forceinline__ float bfhi(unsigned u) { return __uint_as_float(u & 0xffff0000u); }
; __device__ __forceinline__ float geluf_(float x) { const float y = 0.7978845608028654f * (x + 0.044715f * x * x * x); return x * sigmoidf_(2.0f * y); }
; __device__ __forceinline__ float shx(float v, int o, int lane) { return __builtin_bit_cast(float, __builtin_amdgcn_ds_bpermute((lane ^ o) << 2, __builtin_bit_cast(int, v))); }
; __device__ __forceinline__ float wave_sum(float v, int lane) {
; #pragma unroll
;     for (int o = 1; o < 64; o <<= 1) v += shx(v, o, lane);
;     return v;
; }
; __device__ __forceinline__ void sgu_item(LAS unsigned char* lds, const bf16* PROJ, bf16* MIX, const float* lg, const float* lb, const float* ws_, const float* bs_, int item, int tid) {
;     ...
;     for (int q = 0; q < 16; ++q) { const int s = 16 * wid + q; const u32x4 v = *(const u32x4*)(PROJ + (row0 + s) * NPROJ + 512 + lane * 8);
;         float x[8] = {bflo(v.x), bfhi(v.x), bflo(v.y), bfhi(v.y), bflo(v.z), bfhi(v.z), bflo(v.w), bfhi(v.w)}; float sm = 0.f;
; #pragma unroll
;         for (int e = 0; e < 8; ++e) { x[e] = geluf_(x[e]); sm += x[e]; }
;         const float mean = wave_sum(sm, lane) * (1.f / 512.f); float s2 = 0.f;
; #pragma unroll
;         for (int e = 0; e < 8; ++e) { const float d = x[e] - mean; s2 += d * d; }
;         const float rstd = 1.0f / sqrtf(wave_sum(s2, lane) * (1.f / 512.f) + 1e-5f);
;         if (lane == 0) { st[2 * s] = mean; st[2 * s + 1] = rstd; } }
.LBB0_360:
	s_waitcnt vmcnt(0)
	v_mov_b32_e32 v14, v108
	v_mov_b32_e32 v15, v109
	v_mov_b32_e32 v16, v110
	v_mov_b32_e32 v17, v111
	v_lshl_add_u64 v[112:113], v[4:5], 0, s[100:101]
	global_load_dwordx4 v[108:111], v[112:113], off
	v_lshlrev_b32_e32 v0, 16, v14
	s_waitcnt lgkmcnt(0)
	v_and_b32_e32 v7, 0xffff0000, v14
	v_mul_f32_e32 v6, 0x3d372713, v0
	v_lshlrev_b32_e32 v13, 16, v15
	v_mul_f32_e32 v19, 0x3d372713, v7
	v_mul_f32_e32 v6, v6, v0
	v_and_b32_e32 v14, 0xffff0000, v15
	v_mul_f32_e32 v20, 0x3d372713, v13
	v_mul_f32_e32 v19, v19, v7
	v_fma_f32 v6, v6, v0, v0
	v_lshlrev_b32_e32 v15, 16, v16
	v_mul_f32_e32 v21, 0x3d372713, v14
	v_mul_f32_e32 v20, v20, v13
	v_fma_f32 v19, v19, v7, v7
	v_mul_f32_e32 v6, 0x3f4c422a, v6
	v_and_b32_e32 v16, 0xffff0000, v16
	v_mul_f32_e32 v22, 0x3d372713, v15
	v_mul_f32_e32 v21, v21, v14
	v_fma_f32 v20, v20, v13, v13
	v_mul_f32_e32 v19, 0x3f4c422a, v19
	v_add_f32_e32 v6, v6, v6
	v_lshlrev_b32_e32 v18, 16, v17
	v_mul_f32_e32 v23, 0x3d372713, v16
	v_mul_f32_e32 v22, v22, v15
	v_fma_f32 v21, v21, v14, v14
	v_mul_f32_e32 v20, 0x3f4c422a, v20
	v_add_f32_e32 v19, v19, v19
	v_mul_f32_e32 v6, 0xbfb8aa3b, v6
	v_and_b32_e32 v17, 0xffff0000, v17
	v_mul_f32_e32 v24, 0x3d372713, v18
	v_mul_f32_e32 v23, v23, v16
	v_fma_f32 v22, v22, v15, v15
	v_mul_f32_e32 v21, 0x3f4c422a, v21
	v_add_f32_e32 v20, v20, v20
	v_mul_f32_e32 v19, 0xbfb8aa3b, v19
	v_exp_f32_e32 v6, v6
	v_mul_f32_e32 v25, 0x3d372713, v17
	v_mul_f32_e32 v24, v24, v18
	v_fma_f32 v23, v23, v16, v16
	v_mul_f32_e32 v22, 0x3f4c422a, v22
	v_add_f32_e32 v21, v21, v21
	v_mul_f32_e32 v20, 0xbfb8aa3b, v20
	v_exp_f32_e32 v19, v19
	v_mul_f32_e32 v25, v25, v17
	v_fma_f32 v24, v24, v18, v18
	v_mul_f32_e32 v23, 0x3f4c422a, v23
	v_add_f32_e32 v22, v22, v22
	v_mul_f32_e32 v21, 0xbfb8aa3b, v21
	v_exp_f32_e32 v20, v20
	v_fma_f32 v25, v25, v17, v17
	v_mul_f32_e32 v24, 0x3f4c422a, v24
	v_add_f32_e32 v23, v23, v23
	v_mul_f32_e32 v22, 0xbfb8aa3b, v22
	v_exp_f32_e32 v21, v21
	v_mul_f32_e32 v25, 0x3f4c422a, v25
	v_add_f32_e32 v24, v24, v24
	v_mul_f32_e32 v23, 0xbfb8aa3b, v23
	v_exp_f32_e32 v22, v22
	v_add_f32_e32 v6, 1.0, v6
	v_add_f32_e32 v25, v25, v25
	v_mul_f32_e32 v24, 0xbfb8aa3b, v24
	v_exp_f32_e32 v23, v23
	v_add_f32_e32 v19, 1.0, v19
	v_rcp_f32_e32 v26, v6
	v_mul_f32_e32 v25, 0xbfb8aa3b, v25
	v_exp_f32_e32 v24, v24
	v_add_f32_e32 v20, 1.0, v20
	v_rcp_f32_e32 v19, v19
	v_exp_f32_e32 v25, v25
	v_add_f32_e32 v21, 1.0, v21
	v_rcp_f32_e32 v20, v20
	v_add_f32_e32 v22, 1.0, v22
	v_rcp_f32_e32 v21, v21
	v_add_f32_e32 v23, 1.0, v23
	v_rcp_f32_e32 v22, v22
	v_fma_f32 v6, v26, v0, 0
	v_add_f32_e32 v24, 1.0, v24
	v_rcp_f32_e32 v23, v23
	v_fmac_f32_e32 v6, v19, v7
	v_add_f32_e32 v25, 1.0, v25
	v_rcp_f32_e32 v24, v24
	v_fmac_f32_e32 v6, v20, v13
	v_rcp_f32_e32 v25, v25
	v_fmac_f32_e32 v6, v21, v14
	v_fmac_f32_e32 v6, v22, v15
	v_fmac_f32_e32 v6, v23, v16
	v_fmac_f32_e32 v6, v24, v18
	v_fmac_f32_e32 v6, v25, v17
	s_nop 1
	v_add_f32_dpp v6, v6, v6 quad_perm:[1,0,3,2] row_mask:0xf bank_mask:0xf
	s_nop 1
	v_add_f32_dpp v6, v6, v6 quad_perm:[2,3,0,1] row_mask:0xf bank_mask:0xf
	s_nop 1
	v_add_f32_dpp v6, v6, v6 row_half_mirror row_mask:0xf bank_mask:0xf
	s_nop 1
	v_add_f32_dpp v6, v6, v6 row_mirror row_mask:0xf bank_mask:0xf
	ds_bpermute_b32 v27, v11, v6
	s_waitcnt lgkmcnt(0)
	v_add_f32_e32 v6, v6, v27
	ds_bpermute_b32 v27, v12, v6
	s_waitcnt lgkmcnt(0)
	v_add_f32_e32 v6, v6, v27
	v_mul_f32_e32 v6, 0x3b000000, v6
	v_fma_f32 v7, v19, v7, -v6
	v_fma_f32 v0, v26, v0, -v6
	v_mul_f32_e32 v7, v7, v7
	v_fma_f32 v13, v20, v13, -v6
	v_fmac_f32_e32 v7, v0, v0
	v_fma_f32 v14, v21, v14, -v6
	v_fmac_f32_e32 v7, v13, v13
	v_fma_f32 v15, v22, v15, -v6
	v_fmac_f32_e32 v7, v14, v14
	v_fma_f32 v16, v23, v16, -v6
	v_fmac_f32_e32 v7, v15, v15
	v_fma_f32 v18, v24, v18, -v6
	v_fmac_f32_e32 v7, v16, v16
	v_fmac_f32_e32 v7, v18, v18
	v_fma_f32 v0, v25, v17, -v6
	v_fmac_f32_e32 v7, v0, v0
	s_nop 1
	v_add_f32_dpp v0, v7, v7 quad_perm:[1,0,3,2] row_mask:0xf bank_mask:0xf
	s_nop 1
	v_add_f32_dpp v0, v0, v0 quad_perm:[2,3,0,1] row_mask:0xf bank_mask:0xf
	s_nop 1
	v_add_f32_dpp v0, v0, v0 row_half_mirror row_mask:0xf bank_mask:0xf
	s_nop 1
	v_add_f32_dpp v0, v0, v0 row_mirror row_mask:0xf bank_mask:0xf
	ds_bpermute_b32 v7, v11, v0
	s_waitcnt lgkmcnt(0)
	v_add_f32_e32 v0, v0, v7
	ds_bpermute_b32 v7, v12, v0
	s_and_saveexec_b64 s[0:1], s[8:9]
	s_cbranch_execz .LBB0_359
	s_waitcnt lgkmcnt(0)
	v_add_f32_e32 v0, v0, v7
	v_fmamk_f32 v0, v0, 0x3b000000, v232
	v_mul_f32_e32 v7, 0x4f800000, v0
	v_cmp_gt_f32_e32 vcc, s80, v0
	s_add_i32 s5, s4, s3
	s_nop 0
	v_cndmask_b32_e32 v0, v0, v7, vcc
	v_sqrt_f32_e32 v7, v0
	s_nop 0
	v_add_u32_e32 v13, -1, v7
	v_fma_f32 v15, -v13, v7, v0
	v_add_u32_e32 v14, 1, v7
	v_cmp_ge_f32_e64 s[10:11], 0, v15
	s_nop 1
	v_cndmask_b32_e64 v13, v7, v13, s[10:11]
	v_fma_f32 v7, -v14, v7, v0
	v_cmp_lt_f32_e64 s[10:11], 0, v7
	s_nop 1
	v_cndmask_b32_e64 v7, v13, v14, s[10:11]
	v_mul_f32_e32 v13, 0x37800000, v7
	v_cndmask_b32_e32 v7, v7, v13, vcc
	v_cmp_class_f32_e32 vcc, v0, v231
	s_nop 1
	v_cndmask_b32_e32 v0, v7, v0, vcc
	v_div_scale_f32 v7, s[6:7], v0, v0, 1.0
	v_rcp_f32_e32 v13, v7
	s_nop 0
	v_fma_f32 v14, -v7, v13, 1.0
	v_fmac_f32_e32 v13, v14, v13
	v_div_scale_f32 v14, vcc, 1.0, v0, 1.0
	v_mul_f32_e32 v15, v14, v13
	v_fma_f32 v16, -v7, v15, v14
	v_fmac_f32_e32 v15, v16, v13
	v_fma_f32 v7, -v7, v15, v14
	v_div_fmas_f32 v7, v7, v13, v15
	v_div_fixup_f32 v7, v7, v0, 1.0
	v_mov_b32_e32 v0, s5
	ds_write_b64 v0, v[6:7]
	s_branch .LBB0_359

; __device__ __forceinline__ float bf2f(unsigned short b) { return __uint_as_float((unsigned)b << 16); }
; __device__ __forceinline__ float sigmoidf_(float x) { return frcp(1.0f + fexp2(-1.4426950408889634f * x)); }
; __device__ __forceinline__ void conv_item(LAS unsigned char* lds, const bf16* PROJ, bf16* MIX, const float* cw, const float* cb, const float* lg, const float* lb, int item, int tid) {
;     ...
;     float w[31];
; #pragma unroll
;     for (int k = 0; k < 31; ++k) w[k] = cw[k * 512 + c];
;     float hw[62];
; #pragma unroll
;     for (int i = 0; i < 62; ++i) { float hv = 0.f;
;         if (pos0 - 30 + i >= 0) { const bf16* rp = PROJ + (size_t)(row0 - 30 + i) * NPROJ; const float a = bf2f(rp[1536 + c]), g = bf2f(rp[2048 + c]); hv = a * sigmoidf_(g); }
;         hw[i] = hv; }
.LBB0_432:
	s_mov_b64 s[100:101], 0x1400
	v_add_co_u32_e32 v36, vcc, 0xc00, v2
	s_nop 1
	v_addc_co_u32_e32 v37, vcc, 0, v3, vcc
	global_load_ushort v160, v[36:37], off
	global_load_ushort v161, v[36:37], off offset:1024
	v_lshl_add_u64 v[36:37], v[36:37], 0, s[100:101]
	global_load_ushort v162, v[36:37], off
	global_load_ushort v163, v[36:37], off offset:1024
	v_lshl_add_u64 v[36:37], v[36:37], 0, s[100:101]
	global_load_ushort v164, v[36:37], off
	global_load_ushort v165, v[36:37], off offset:1024
	v_lshl_add_u64 v[36:37], v[36:37], 0, s[100:101]
	global_load_ushort v166, v[36:37], off
	global_load_ushort v167, v[36:37], off offset:1024
	v_lshl_add_u64 v[36:37], v[36:37], 0, s[100:101]
	global_load_ushort v168, v[36:37], off
	global_load_ushort v169, v[36:37], off offset:1024
	v_lshl_add_u64 v[36:37], v[36:37], 0, s[100:101]
	global_load_ushort v170, v[36:37], off
	global_load_ushort v171, v[36:37], off offset:1024
	v_lshl_add_u64 v[36:37], v[36:37], 0, s[100:101]
	global_load_ushort v172, v[36:37], off
	global_load_ushort v173, v[36:37], off offset:1024
	v_lshl_add_u64 v[36:37], v[36:37], 0, s[100:101]
	global_load_ushort v174, v[36:37], off
	global_load_ushort v175, v[36:37], off offset:1024
	v_lshl_add_u64 v[36:37], v[36:37], 0, s[100:101]
	global_load_ushort v176, v[36:37], off
	global_load_ushort v177, v[36:37], off offset:1024
	v_lshl_add_u64 v[36:37], v[36:37], 0, s[100:101]
	global_load_ushort v178, v[36:37], off
	global_load_ushort v179, v[36:37], off offset:1024
	v_lshl_add_u64 v[36:37], v[36:37], 0, s[100:101]
	global_load_ushort v180, v[36:37], off
	global_load_ushort v181, v[36:37], off offset:1024
	v_lshl_add_u64 v[36:37], v[36:37], 0, s[100:101]
	global_load_ushort v182, v[36:37], off
	global_load_ushort v183, v[36:37], off offset:1024
	v_lshl_add_u64 v[36:37], v[36:37], 0, s[100:101]
	global_load_ushort v184, v[36:37], off
	global_load_ushort v185, v[36:37], off offset:1024
	v_lshl_add_u64 v[36:37], v[36:37], 0, s[100:101]
	global_load_ushort v186, v[36:37], off
	global_load_ushort v187, v[36:37], off offset:1024
	v_lshl_add_u64 v[36:37], v[36:37], 0, s[100:101]
	global_load_ushort v188, v[36:37], off
	global_load_ushort v189, v[36:37], off offset:1024
	v_lshl_add_u64 v[36:37], v[36:37], 0, s[100:101]
	global_load_ushort v190, v[36:37], off
	global_load_ushort v191, v[36:37], off offset:1024
	v_lshl_add_u64 v[36:37], v[36:37], 0, s[100:101]
	global_load_ushort v192, v[36:37], off
	global_load_ushort v193, v[36:37], off offset:1024
	v_lshl_add_u64 v[36:37], v[36:37], 0, s[100:101]
	global_load_ushort v194, v[36:37], off
	global_load_ushort v195, v[36:37], off offset:1024
	v_lshl_add_u64 v[36:37], v[36:37], 0, s[100:101]
	global_load_ushort v196, v[36:37], off
	global_load_ushort v197, v[36:37], off offset:1024
	v_lshl_add_u64 v[36:37], v[36:37], 0, s[100:101]
	global_load_ushort v198, v[36:37], off
	global_load_ushort v199, v[36:37], off offset:1024
	v_lshl_add_u64 v[36:37], v[36:37], 0, s[100:101]
	global_load_ushort v202, v[36:37], off
	global_load_ushort v203, v[36:37], off offset:1024
	v_lshl_add_u64 v[36:37], v[36:37], 0, s[100:101]
	global_load_ushort v204, v[36:37], off
	global_load_ushort v205, v[36:37], off offset:1024
	v_lshl_add_u64 v[36:37], v[36:37], 0, s[100:101]
	global_load_ushort v206, v[36:37], off
	global_load_ushort v207, v[36:37], off offset:1024
	v_lshl_add_u64 v[36:37], v[36:37], 0, s[100:101]
	global_load_ushort v208, v[36:37], off
	global_load_ushort v209, v[36:37], off offset:1024
	v_lshl_add_u64 v[36:37], v[36:37], 0, s[100:101]
	global_load_ushort v210, v[36:37], off
	global_load_ushort v211, v[36:37], off offset:1024
	v_lshl_add_u64 v[36:37], v[36:37], 0, s[100:101]
	global_load_ushort v212, v[36:37], off
	global_load_ushort v213, v[36:37], off offset:1024
	v_lshl_add_u64 v[36:37], v[36:37], 0, s[100:101]
	global_load_ushort v214, v[36:37], off
	global_load_ushort v215, v[36:37], off offset:1024
	v_lshl_add_u64 v[36:37], v[36:37], 0, s[100:101]
	global_load_ushort v216, v[36:37], off
	global_load_ushort v217, v[36:37], off offset:1024
	v_lshl_add_u64 v[36:37], v[36:37], 0, s[100:101]
	global_load_ushort v218, v[36:37], off
	global_load_ushort v219, v[36:37], off offset:1024
	v_lshl_add_u64 v[36:37], v[36:37], 0, s[100:101]
	global_load_ushort v220, v[36:37], off
	global_load_ushort v221, v[36:37], off offset:1024
	v_lshl_add_u64 v[36:37], v[36:37], 0, s[100:101]
	global_load_ushort v222, v[36:37], off
	global_load_ushort v223, v[36:37], off offset:1024
	v_lshl_add_u64 v[36:37], v[36:37], 0, s[100:101]
	global_load_ushort v224, v[36:37], off
	global_load_ushort v225, v[36:37], off offset:1024
	s_waitcnt vmcnt(0)
	v_add_co_u32_e32 v36, vcc, 0x1000, v2
	v_mov_b32_e32 v34, v160
	s_nop 0
	v_addc_co_u32_e32 v37, vcc, 0, v3, vcc
	v_mov_b32_e32 v36, v161
	v_add_co_u32_e32 v56, vcc, 0x2000, v2
	s_movk_i32 s3, 0x4000
	s_nop 0
	v_addc_co_u32_e32 v57, vcc, 0, v3, vcc
	v_readlane_b32 s0, v255, 20
	v_readlane_b32 s1, v255, 21
	s_lshl_b64 s[14:15], s[0:1], 2
	s_add_u32 s0, s18, s14
	s_addc_u32 s1, s19, s15
	v_and_b32_e32 v35, 63, v200
	v_cmp_eq_u32_e64 s[8:9], 0, v35
	s_waitcnt vmcnt(1)
	v_lshlrev_b32_e32 v34, 16, v34
	s_waitcnt vmcnt(0)
	v_lshlrev_b32_e32 v36, 16, v36
	v_mul_f32_e32 v36, 0xbfb8aa3b, v36
	v_exp_f32_e32 v36, v36
	s_nop 0
	v_add_f32_e32 v36, 1.0, v36
	v_rcp_f32_e32 v36, v36
	s_nop 0
	v_mul_f32_e32 v37, v36, v34
	v_mov_b32_e32 v36, v163
	v_mov_b32_e32 v34, v162
	v_add_co_u32_e32 v56, vcc, 0x3000, v2
	s_waitcnt vmcnt(1)
	v_lshlrev_b32_e32 v36, 16, v36
	v_addc_co_u32_e32 v57, vcc, 0, v3, vcc
	v_mul_f32_e32 v36, 0xbfb8aa3b, v36
	v_mov_b32_e32 v39, v165
	v_exp_f32_e32 v36, v36
	s_waitcnt vmcnt(1)
; __device__ __forceinline__ float bf2f(unsigned short b) { return __uint_as_float((unsigned)b << 16); }
; __device__ __forceinline__ float sigmoidf_(float x) { return frcp(1.0f + fexp2(-1.4426950408889634f * x)); }
; __device__ __forceinline__ void conv_item(LAS unsigned char* lds, const bf16* PROJ, bf16* MIX, const float* cw, const float* cb, const float* lg, const float* lb, int item, int tid) {
;     ...
;     for (int i = 0; i < 62; ++i) { float hv = 0.f;
;         if (pos0 - 30 + i >= 0) { const bf16* rp = PROJ + (size_t)(row0 - 30 + i) * NPROJ; const float a = bf2f(rp[1536 + c]), g = bf2f(rp[2048 + c]); hv = a * sigmoidf_(g); }
;         hw[i] = hv; }
	v_lshlrev_b32_e32 v34, 16, v34
	v_add_f32_e32 v36, 1.0, v36
	v_rcp_f32_e32 v36, v36
	s_waitcnt vmcnt(0)
	v_lshlrev_b32_e32 v39, 16, v39
	v_mul_f32_e32 v36, v36, v34
	v_mov_b32_e32 v34, v164
	v_add_co_u32_e32 v56, vcc, s3, v2
	v_mul_f32_e32 v39, 0xbfb8aa3b, v39
	s_nop 0
	v_addc_co_u32_e32 v57, vcc, 0, v3, vcc
	v_mov_b32_e32 v42, v167
	v_exp_f32_e32 v39, v39
	s_movk_i32 s3, 0x7000
	v_add_f32_e32 v39, 1.0, v39
	v_rcp_f32_e32 v39, v39
	s_waitcnt vmcnt(1)
	v_lshlrev_b32_e32 v34, 16, v34
	v_mul_f32_e32 v39, v39, v34
	v_mov_b32_e32 v34, v166
	v_add_co_u32_e32 v56, vcc, s35, v2
	s_waitcnt vmcnt(1)
	v_lshlrev_b32_e32 v42, 16, v42
	v_mul_f32_e32 v42, 0xbfb8aa3b, v42
	v_exp_f32_e32 v42, v42
	v_addc_co_u32_e32 v57, vcc, 0, v3, vcc
	v_add_f32_e32 v42, 1.0, v42
	v_rcp_f32_e32 v42, v42
	s_waitcnt vmcnt(0)
	v_lshlrev_b32_e32 v34, 16, v34
	v_mul_f32_e32 v42, v42, v34
	v_mov_b32_e32 v34, v168
	v_add_co_u32_e32 v56, vcc, s3, v2
	s_mov_b32 s3, 0x9000
	s_nop 0
	v_addc_co_u32_e32 v57, vcc, 0, v3, vcc
	v_mov_b32_e32 v47, v169
	v_mov_b32_e32 v48, v171
	s_waitcnt vmcnt(2)
	v_lshlrev_b32_e32 v34, 16, v34
	s_waitcnt vmcnt(1)
	v_lshlrev_b32_e32 v47, 16, v47
	v_mul_f32_e32 v47, 0xbfb8aa3b, v47
	v_exp_f32_e32 v47, v47
	s_waitcnt vmcnt(0)
	v_lshlrev_b32_e32 v48, 16, v48
	v_mul_f32_e32 v48, 0xbfb8aa3b, v48
	v_exp_f32_e32 v48, v48
	v_add_f32_e32 v47, 1.0, v47
	v_rcp_f32_e32 v47, v47
	v_add_f32_e32 v48, 1.0, v48
	v_rcp_f32_e32 v48, v48
	v_mul_f32_e32 v47, v47, v34
	v_mov_b32_e32 v34, v170
	v_add_co_u32_e32 v56, vcc, s37, v2
	s_waitcnt vmcnt(0)
	v_lshlrev_b32_e32 v34, 16, v34
	v_addc_co_u32_e32 v57, vcc, 0, v3, vcc
	v_mov_b32_e32 v53, v173
	v_mul_f32_e32 v48, v48, v34
	v_mov_b32_e32 v34, v172
	v_add_co_u32_e32 v56, vcc, s3, v2
	s_mov_b32 s3, 0xd000
	s_nop 0
	v_addc_co_u32_e32 v57, vcc, 0, v3, vcc
	v_add_co_u32_e32 v58, vcc, s38, v2
	s_waitcnt vmcnt(1)
	v_lshlrev_b32_e32 v53, 16, v53
	v_mul_f32_e32 v53, 0xbfb8aa3b, v53
	v_exp_f32_e32 v53, v53
	s_waitcnt vmcnt(0)
	v_lshlrev_b32_e32 v34, 16, v34
	v_addc_co_u32_e32 v59, vcc, 0, v3, vcc
	v_add_f32_e32 v53, 1.0, v53
	v_rcp_f32_e32 v53, v53
	s_nop 0
	v_mul_f32_e32 v53, v53, v34
	v_mov_b32_e32 v34, v174
	s_waitcnt vmcnt(0)
	v_lshlrev_b32_e32 v34, 16, v34
	v_mov_b32_e32 v56, v175
	s_waitcnt vmcnt(0)
	v_lshlrev_b32_e32 v56, 16, v56
	v_mul_f32_e32 v56, 0xbfb8aa3b, v56
	v_exp_f32_e32 v56, v56
	s_nop 0
	v_add_f32_e32 v56, 1.0, v56
	v_rcp_f32_e32 v56, v56
	s_nop 0
	v_mul_f32_e32 v56, v56, v34
	v_mov_b32_e32 v34, v176
	v_add_co_u32_e32 v58, vcc, s39, v2
	s_waitcnt vmcnt(0)
	v_lshlrev_b32_e32 v34, 16, v34
	v_addc_co_u32_e32 v59, vcc, 0, v3, vcc
	v_mov_b32_e32 v57, v177
	v_add_co_u32_e32 v60, vcc, s3, v2
	s_mov_b32 s3, 0x11000
	s_nop 0
	v_addc_co_u32_e32 v61, vcc, 0, v3, vcc
	s_waitcnt vmcnt(0)
	v_lshlrev_b32_e32 v57, 16, v57
	v_mul_f32_e32 v57, 0xbfb8aa3b, v57
	v_exp_f32_e32 v57, v57
	s_nop 0
	v_add_f32_e32 v57, 1.0, v57
	v_rcp_f32_e32 v57, v57
	s_nop 0
	v_mul_f32_e32 v57, v57, v34
	v_mov_b32_e32 v34, v178
	s_waitcnt vmcnt(0)
	v_lshlrev_b32_e32 v34, 16, v34
	v_mov_b32_e32 v58, v179
	s_waitcnt vmcnt(0)
	v_lshlrev_b32_e32 v58, 16, v58
	v_mul_f32_e32 v58, 0xbfb8aa3b, v58
	v_mov_b32_e32 v59, v181
	v_exp_f32_e32 v58, v58
	s_waitcnt vmcnt(0)
	v_lshlrev_b32_e32 v59, 16, v59
	v_add_f32_e32 v58, 1.0, v58
	v_rcp_f32_e32 v58, v58
	v_mul_f32_e32 v59, 0xbfb8aa3b, v59
	v_exp_f32_e32 v59, v59
	v_mul_f32_e32 v58, v58, v34
	v_mov_b32_e32 v34, v180
	v_add_f32_e32 v59, 1.0, v59
	v_rcp_f32_e32 v59, v59
	v_add_co_u32_e32 v60, vcc, s42, v2
	s_waitcnt vmcnt(0)
	v_lshlrev_b32_e32 v34, 16, v34
	v_addc_co_u32_e32 v61, vcc, 0, v3, vcc
	v_mul_f32_e32 v59, v59, v34
	v_mov_b32_e32 v34, v182
	v_add_co_u32_e32 v66, vcc, s44, v2
	v_mov_b32_e32 v60, v183
	s_nop 0
	v_addc_co_u32_e32 v67, vcc, 0, v3, vcc
	s_waitcnt vmcnt(1)
	v_lshlrev_b32_e32 v34, 16, v34
	s_waitcnt vmcnt(0)
	v_lshlrev_b32_e32 v60, 16, v60
	v_mul_f32_e32 v60, 0xbfb8aa3b, v60
	v_exp_f32_e32 v60, v60
	s_nop 0
	v_add_f32_e32 v60, 1.0, v60
	v_rcp_f32_e32 v60, v60
	s_nop 0
	v_mul_f32_e32 v60, v60, v34
	v_mov_b32_e32 v34, v184
	v_add_co_u32_e32 v66, vcc, s3, v2
	s_mov_b32 s3, 0x12000
	s_nop 0
	v_addc_co_u32_e32 v67, vcc, 0, v3, vcc
	v_mov_b32_e32 v61, v185
	v_mov_b32_e32 v63, v187
	s_waitcnt vmcnt(2)
	v_lshlrev_b32_e32 v34, 16, v34
	s_waitcnt vmcnt(1)
	v_lshlrev_b32_e32 v61, 16, v61
	v_mul_f32_e32 v61, 0xbfb8aa3b, v61
	v_exp_f32_e32 v61, v61
	s_waitcnt vmcnt(0)
	v_lshlrev_b32_e32 v63, 16, v63
	v_mul_f32_e32 v63, 0xbfb8aa3b, v63
	v_exp_f32_e32 v63, v63
	v_add_f32_e32 v61, 1.0, v61
	v_rcp_f32_e32 v61, v61
	v_add_f32_e32 v63, 1.0, v63
	v_rcp_f32_e32 v63, v63
	v_mul_f32_e32 v61, v61, v34
	v_mov_b32_e32 v34, v186
	v_add_co_u32_e32 v66, vcc, s3, v2
	s_mov_b32 s3, 0x13000
	s_nop 0
	v_addc_co_u32_e32 v67, vcc, 0, v3, vcc
	v_mov_b32_e32 v65, v189
	s_waitcnt vmcnt(1)
	v_lshlrev_b32_e32 v34, 16, v34
	v_mul_f32_e32 v63, v63, v34
	v_mov_b32_e32 v34, v188
	v_add_co_u32_e32 v66, vcc, s3, v2
	s_mov_b32 s3, 0x14000
	s_waitcnt vmcnt(1)
	v_lshlrev_b32_e32 v65, 16, v65
	v_mul_f32_e32 v65, 0xbfb8aa3b, v65
	v_exp_f32_e32 v65, v65
	v_addc_co_u32_e32 v67, vcc, 0, v3, vcc
	v_add_co_u32_e32 v72, vcc, s3, v2
	v_add_f32_e32 v65, 1.0, v65
	v_rcp_f32_e32 v65, v65
	v_addc_co_u32_e32 v73, vcc, 0, v3, vcc
	s_mov_b32 s3, 0x17000
	s_waitcnt vmcnt(0)
	v_lshlrev_b32_e32 v34, 16, v34
	v_mul_f32_e32 v65, v65, v34
	v_mov_b32_e32 v34, v190
	s_waitcnt vmcnt(0)
	v_lshlrev_b32_e32 v34, 16, v34
	v_mov_b32_e32 v66, v191
	s_waitcnt vmcnt(0)
	v_lshlrev_b32_e32 v66, 16, v66
	v_mul_f32_e32 v66, 0xbfb8aa3b, v66
	v_exp_f32_e32 v66, v66
	s_nop 0
	v_add_f32_e32 v66, 1.0, v66
	v_rcp_f32_e32 v66, v66
	s_nop 0
	v_mul_f32_e32 v66, v66, v34
	v_mov_b32_e32 v34, v192
	v_add_co_u32_e32 v72, vcc, s36, v2
	s_waitcnt vmcnt(0)
; __device__ __forceinline__ float bf2f(unsigned short b) { return __uint_as_float((unsigned)b << 16); }
; __device__ __forceinline__ float sigmoidf_(float x) { return frcp(1.0f + fexp2(-1.4426950408889634f * x)); }
; __device__ __forceinline__ void conv_item(LAS unsigned char* lds, const bf16* PROJ, bf16* MIX, const float* cw, const float* cb, const float* lg, const float* lb, int item, int tid) {
;     ...
;     for (int i = 0; i < 62; ++i) { float hv = 0.f;
;         if (pos0 - 30 + i >= 0) { const bf16* rp = PROJ + (size_t)(row0 - 30 + i) * NPROJ; const float a = bf2f(rp[1536 + c]), g = bf2f(rp[2048 + c]); hv = a * sigmoidf_(g); }
;         hw[i] = hv; }
	v_lshlrev_b32_e32 v34, 16, v34
	v_addc_co_u32_e32 v73, vcc, 0, v3, vcc
	v_mov_b32_e32 v67, v193
	v_mov_b32_e32 v68, v195
	s_waitcnt vmcnt(1)
	v_lshlrev_b32_e32 v67, 16, v67
	v_mul_f32_e32 v67, 0xbfb8aa3b, v67
	v_exp_f32_e32 v67, v67
	s_waitcnt vmcnt(0)
	v_lshlrev_b32_e32 v68, 16, v68
	v_mul_f32_e32 v68, 0xbfb8aa3b, v68
	v_exp_f32_e32 v68, v68
	v_add_f32_e32 v67, 1.0, v67
	v_rcp_f32_e32 v67, v67
	v_add_f32_e32 v68, 1.0, v68
	v_rcp_f32_e32 v68, v68
	v_mul_f32_e32 v67, v67, v34
	v_mov_b32_e32 v34, v194
	v_add_co_u32_e32 v72, vcc, s3, v2
	s_mov_b32 s3, 0x18000
	s_nop 0
	v_addc_co_u32_e32 v73, vcc, 0, v3, vcc
	v_mov_b32_e32 v71, v197
	s_waitcnt vmcnt(1)
	v_lshlrev_b32_e32 v34, 16, v34
	v_mul_f32_e32 v68, v68, v34
	v_mov_b32_e32 v34, v196
	v_add_co_u32_e32 v72, vcc, s3, v2
	s_mov_b32 s3, 0x19000
	s_waitcnt vmcnt(1)
	v_lshlrev_b32_e32 v71, 16, v71
	v_mul_f32_e32 v71, 0xbfb8aa3b, v71
	v_exp_f32_e32 v71, v71
	v_addc_co_u32_e32 v73, vcc, 0, v3, vcc
	v_add_co_u32_e32 v74, vcc, s3, v2
	v_add_f32_e32 v71, 1.0, v71
	v_rcp_f32_e32 v71, v71
	v_addc_co_u32_e32 v75, vcc, 0, v3, vcc
	s_mov_b32 s3, 0x1c000
	s_waitcnt vmcnt(0)
	v_lshlrev_b32_e32 v34, 16, v34
	v_mul_f32_e32 v71, v71, v34
	v_mov_b32_e32 v34, v198
	s_waitcnt vmcnt(0)
	v_lshlrev_b32_e32 v34, 16, v34
	v_mov_b32_e32 v72, v199
	s_waitcnt vmcnt(0)
	v_lshlrev_b32_e32 v72, 16, v72
	v_mul_f32_e32 v72, 0xbfb8aa3b, v72
	v_exp_f32_e32 v72, v72
	s_nop 0
	v_add_f32_e32 v72, 1.0, v72
	v_rcp_f32_e32 v72, v72
	s_nop 0
	v_mul_f32_e32 v72, v72, v34
	v_mov_b32_e32 v34, v202
	v_add_co_u32_e32 v74, vcc, s52, v2
	s_waitcnt vmcnt(0)
	v_lshlrev_b32_e32 v34, 16, v34
	v_addc_co_u32_e32 v75, vcc, 0, v3, vcc
	v_mov_b32_e32 v73, v203
	v_add_co_u32_e32 v88, vcc, s3, v2
	s_mov_b32 s3, 0x1d000
	s_nop 0
	v_addc_co_u32_e32 v89, vcc, 0, v3, vcc
	s_waitcnt vmcnt(0)
	v_lshlrev_b32_e32 v73, 16, v73
	v_mul_f32_e32 v73, 0xbfb8aa3b, v73
	v_exp_f32_e32 v73, v73
	s_nop 0
	v_add_f32_e32 v73, 1.0, v73
	v_rcp_f32_e32 v73, v73
	s_nop 0
	v_mul_f32_e32 v73, v73, v34
	v_mov_b32_e32 v34, v204
	s_waitcnt vmcnt(0)
	v_lshlrev_b32_e32 v34, 16, v34
	v_mov_b32_e32 v74, v205
	s_waitcnt vmcnt(0)
	v_lshlrev_b32_e32 v74, 16, v74
	v_mul_f32_e32 v74, 0xbfb8aa3b, v74
	v_mov_b32_e32 v75, v207
	v_exp_f32_e32 v74, v74
	s_waitcnt vmcnt(0)
	v_lshlrev_b32_e32 v75, 16, v75
	v_add_f32_e32 v74, 1.0, v74
	v_rcp_f32_e32 v74, v74
	v_mul_f32_e32 v75, 0xbfb8aa3b, v75
	v_exp_f32_e32 v75, v75
	v_mul_f32_e32 v74, v74, v34
	v_mov_b32_e32 v34, v206
	v_add_co_u32_e32 v88, vcc, s3, v2
	v_add_f32_e32 v75, 1.0, v75
	s_nop 0
	v_addc_co_u32_e32 v89, vcc, 0, v3, vcc
	v_mov_b32_e32 v76, v209
	v_rcp_f32_e32 v75, v75
	s_mov_b32 s3, 0x1e000
	s_waitcnt vmcnt(1)
	v_lshlrev_b32_e32 v34, 16, v34
	v_mul_f32_e32 v75, v75, v34
	v_mov_b32_e32 v34, v208
	v_add_co_u32_e32 v88, vcc, s3, v2
	s_mov_b32 s3, 0x20000
	s_waitcnt vmcnt(1)
	v_lshlrev_b32_e32 v76, 16, v76
	v_mul_f32_e32 v76, 0xbfb8aa3b, v76
	v_exp_f32_e32 v76, v76
	v_addc_co_u32_e32 v89, vcc, 0, v3, vcc
	v_add_f32_e32 v76, 1.0, v76
	v_rcp_f32_e32 v76, v76
	s_waitcnt vmcnt(0)
	v_lshlrev_b32_e32 v34, 16, v34
	v_mul_f32_e32 v76, v76, v34
	v_mov_b32_e32 v34, v210
	v_add_co_u32_e32 v88, vcc, s3, v2
	s_mov_b32 s3, 0x22000
	s_nop 0
	v_addc_co_u32_e32 v89, vcc, 0, v3, vcc
	v_mov_b32_e32 v87, v211
	v_add_co_u32_e32 v94, vcc, s53, v2
	s_waitcnt vmcnt(1)
	v_lshlrev_b32_e32 v34, 16, v34
	v_addc_co_u32_e32 v95, vcc, 0, v3, vcc
	s_waitcnt vmcnt(0)
	v_lshlrev_b32_e32 v87, 16, v87
	v_mul_f32_e32 v87, 0xbfb8aa3b, v87
	v_exp_f32_e32 v87, v87
	s_nop 0
	v_add_f32_e32 v87, 1.0, v87
	v_rcp_f32_e32 v87, v87
	s_nop 0
	v_mul_f32_e32 v87, v87, v34
	v_mov_b32_e32 v34, v212
	s_waitcnt vmcnt(0)
	v_lshlrev_b32_e32 v34, 16, v34
	v_mov_b32_e32 v88, v213
	s_waitcnt vmcnt(0)
	v_lshlrev_b32_e32 v88, 16, v88
	v_mul_f32_e32 v88, 0xbfb8aa3b, v88
	v_mov_b32_e32 v89, v215
	v_exp_f32_e32 v88, v88
	s_waitcnt vmcnt(0)
	v_lshlrev_b32_e32 v89, 16, v89
	v_add_f32_e32 v88, 1.0, v88
	v_rcp_f32_e32 v88, v88
	v_mul_f32_e32 v89, 0xbfb8aa3b, v89
	v_exp_f32_e32 v89, v89
	v_mul_f32_e32 v88, v88, v34
	v_mov_b32_e32 v34, v214
	v_add_co_u32_e32 v94, vcc, s3, v2
	v_add_f32_e32 v89, 1.0, v89
	s_nop 0
	v_addc_co_u32_e32 v95, vcc, 0, v3, vcc
	v_mov_b32_e32 v92, v217
	v_rcp_f32_e32 v89, v89
	s_mov_b32 s3, 0x23000
	s_waitcnt vmcnt(1)
	v_lshlrev_b32_e32 v34, 16, v34
	v_mul_f32_e32 v89, v89, v34
	v_mov_b32_e32 v34, v216
	v_add_co_u32_e32 v94, vcc, s3, v2
	s_mov_b32 s3, 0x25000
	s_waitcnt vmcnt(1)
	v_lshlrev_b32_e32 v92, 16, v92
	v_mul_f32_e32 v92, 0xbfb8aa3b, v92
	v_exp_f32_e32 v92, v92
	v_addc_co_u32_e32 v95, vcc, 0, v3, vcc
	v_add_co_u32_e32 v96, vcc, s3, v2
	v_add_f32_e32 v92, 1.0, v92
	v_rcp_f32_e32 v92, v92
	v_addc_co_u32_e32 v97, vcc, 0, v3, vcc
	s_mov_b32 s3, 0x27000
	s_waitcnt vmcnt(0)
	v_lshlrev_b32_e32 v34, 16, v34
	v_mul_f32_e32 v92, v92, v34
	v_mov_b32_e32 v34, v218
	s_waitcnt vmcnt(0)
	v_lshlrev_b32_e32 v34, 16, v34
	v_mov_b32_e32 v94, v219
	v_mov_b32_e32 v95, v221
	s_waitcnt vmcnt(1)
	v_lshlrev_b32_e32 v94, 16, v94
	v_mul_f32_e32 v94, 0xbfb8aa3b, v94
	v_exp_f32_e32 v94, v94
	s_waitcnt vmcnt(0)
	v_lshlrev_b32_e32 v95, 16, v95
	v_mul_f32_e32 v95, 0xbfb8aa3b, v95
	v_exp_f32_e32 v95, v95
	v_add_f32_e32 v94, 1.0, v94
	v_rcp_f32_e32 v94, v94
	v_add_f32_e32 v95, 1.0, v95
	v_rcp_f32_e32 v95, v95
	v_mul_f32_e32 v94, v94, v34
	v_mov_b32_e32 v34, v220
	v_add_co_u32_e32 v96, vcc, s55, v2
	s_waitcnt vmcnt(0)
	v_lshlrev_b32_e32 v34, 16, v34
	v_addc_co_u32_e32 v97, vcc, 0, v3, vcc
	v_mul_f32_e32 v95, v95, v34
	v_mov_b32_e32 v34, v222
	v_add_co_u32_e32 v2, vcc, s3, v2
	v_mov_b32_e32 v96, v223
	s_nop 0
	v_addc_co_u32_e32 v3, vcc, 0, v3, vcc
	s_waitcnt vmcnt(1)
	v_lshlrev_b32_e32 v34, 16, v34
	s_waitcnt vmcnt(0)
; __device__ __forceinline__ float bf2f(unsigned short b) { return __uint_as_float((unsigned)b << 16); }
; __device__ __forceinline__ float sigmoidf_(float x) { return frcp(1.0f + fexp2(-1.4426950408889634f * x)); }
; __device__ __forceinline__ void conv_item(LAS unsigned char* lds, const bf16* PROJ, bf16* MIX, const float* cw, const float* cb, const float* lg, const float* lb, int item, int tid) {
;     ...
;     for (int i = 0; i < 62; ++i) { float hv = 0.f;
;         if (pos0 - 30 + i >= 0) { const bf16* rp = PROJ + (size_t)(row0 - 30 + i) * NPROJ; const float a = bf2f(rp[1536 + c]), g = bf2f(rp[2048 + c]); hv = a * sigmoidf_(g); }
;         hw[i] = hv; }
;     float acc[32]; const float bias = cb[c];
; #pragma unroll
;     for (int tk = 0; tk < 32; ++tk) { float s = bias;
; #pragma unroll
;         for (int k = 0; k < 31; ++k) s += w[k] * hw[tk + k];
;         acc[tk] = s; }
	v_lshlrev_b32_e32 v96, 16, v96
	v_mul_f32_e32 v96, 0xbfb8aa3b, v96
	v_exp_f32_e32 v96, v96
	s_nop 0
	v_add_f32_e32 v96, 1.0, v96
	v_rcp_f32_e32 v96, v96
	s_nop 0
	v_mul_f32_e32 v96, v96, v34
	v_mov_b32_e32 v34, v225
	s_waitcnt vmcnt(0)
	v_lshlrev_b32_e32 v34, 16, v34
	v_mov_b32_e32 v2, v224
	v_mul_f32_e32 v34, 0xbfb8aa3b, v34
	v_exp_f32_e32 v34, v34
	s_waitcnt vmcnt(0)
	v_lshlrev_b32_e32 v2, 16, v2
	v_add_f32_e32 v34, 1.0, v34
	v_rcp_f32_e32 v34, v34
	s_nop 0
	v_mul_f32_e32 v97, v34, v2
	v_lshl_add_u64 v[2:3], v[200:201], 2, s[0:1]
	global_load_dword v34, v[2:3], off
	v_readfirstlane_b32 s0, v200
	s_ashr_i32 s3, s0, 4
	s_and_b32 s4, s3, -4
	s_waitcnt vmcnt(0)
	v_fma_f32 v93, v10, v93, v34
	v_fmac_f32_e32 v93, v9, v90
	v_fma_f32 v90, v10, v90, v34
	v_fmac_f32_e32 v93, v8, v91
	v_fmac_f32_e32 v90, v9, v91
	v_fma_f32 v2, v10, v91, v34
	v_fmac_f32_e32 v93, v7, v86
	v_fmac_f32_e32 v90, v8, v86
	v_fmac_f32_e32 v2, v9, v86
	v_fma_f32 v86, v10, v86, v34
	v_fmac_f32_e32 v93, v5, v85
	v_fmac_f32_e32 v90, v7, v85
	v_fmac_f32_e32 v2, v8, v85
	v_fmac_f32_e32 v86, v9, v85
	v_fma_f32 v3, v10, v85, v34
	v_fmac_f32_e32 v93, v0, v84
	v_fmac_f32_e32 v90, v5, v84
	v_fmac_f32_e32 v2, v7, v84
	v_fmac_f32_e32 v86, v8, v84
	v_fmac_f32_e32 v3, v9, v84
	v_fma_f32 v84, v10, v84, v34
	v_fmac_f32_e32 v93, v6, v83
	v_fmac_f32_e32 v90, v0, v83
	v_fmac_f32_e32 v2, v5, v83
	v_fmac_f32_e32 v86, v7, v83
	v_fmac_f32_e32 v3, v8, v83
	v_fmac_f32_e32 v84, v9, v83
	v_fma_f32 v83, v10, v83, v34
	v_fmac_f32_e32 v93, v4, v82
	v_fmac_f32_e32 v90, v6, v82
	v_fmac_f32_e32 v2, v0, v82
	v_fmac_f32_e32 v86, v5, v82
	v_fmac_f32_e32 v3, v7, v82
	v_fmac_f32_e32 v84, v8, v82
	v_fmac_f32_e32 v83, v9, v82
	v_fma_f32 v82, v10, v82, v34
	v_fmac_f32_e32 v93, v18, v81
	v_fmac_f32_e32 v90, v4, v81
	v_fmac_f32_e32 v2, v6, v81
	v_fmac_f32_e32 v86, v0, v81
	v_fmac_f32_e32 v3, v5, v81
	v_fmac_f32_e32 v84, v7, v81
	v_fmac_f32_e32 v83, v8, v81
	v_fmac_f32_e32 v82, v9, v81
	v_fma_f32 v81, v10, v81, v34
	v_fmac_f32_e32 v93, v17, v80
	v_fmac_f32_e32 v90, v18, v80
	v_fmac_f32_e32 v2, v4, v80
	v_fmac_f32_e32 v86, v6, v80
	v_fmac_f32_e32 v3, v0, v80
	v_fmac_f32_e32 v84, v5, v80
	v_fmac_f32_e32 v83, v7, v80
	v_fmac_f32_e32 v82, v8, v80
	v_fmac_f32_e32 v81, v9, v80
	v_fma_f32 v80, v10, v80, v34
	v_fmac_f32_e32 v93, v33, v79
	v_fmac_f32_e32 v90, v17, v79
	v_fmac_f32_e32 v2, v18, v79
	v_fmac_f32_e32 v86, v4, v79
	v_fmac_f32_e32 v3, v6, v79
	v_fmac_f32_e32 v84, v0, v79
	v_fmac_f32_e32 v83, v5, v79
	v_fmac_f32_e32 v82, v7, v79
	v_fmac_f32_e32 v81, v8, v79
	v_fmac_f32_e32 v80, v9, v79
	v_fma_f32 v79, v10, v79, v34
	v_fmac_f32_e32 v93, v16, v78
	v_fmac_f32_e32 v90, v33, v78
	v_fmac_f32_e32 v2, v17, v78
	v_fmac_f32_e32 v86, v18, v78
	v_fmac_f32_e32 v3, v4, v78
	v_fmac_f32_e32 v84, v6, v78
	v_fmac_f32_e32 v83, v0, v78
	v_fmac_f32_e32 v82, v5, v78
	v_fmac_f32_e32 v81, v7, v78
	v_fmac_f32_e32 v80, v8, v78
	v_fmac_f32_e32 v79, v9, v78
	v_fma_f32 v78, v10, v78, v34
	v_fmac_f32_e32 v93, v32, v77
	v_fmac_f32_e32 v90, v16, v77
	v_fmac_f32_e32 v2, v33, v77
	v_fmac_f32_e32 v86, v17, v77
	v_fmac_f32_e32 v3, v18, v77
	v_fmac_f32_e32 v84, v4, v77
	v_fmac_f32_e32 v83, v6, v77
	v_fmac_f32_e32 v82, v0, v77
	v_fmac_f32_e32 v81, v5, v77
	v_fmac_f32_e32 v80, v7, v77
	v_fmac_f32_e32 v79, v8, v77
	v_fmac_f32_e32 v78, v9, v77
	v_fma_f32 v77, v10, v77, v34
	v_fmac_f32_e32 v93, v31, v70
	v_fmac_f32_e32 v90, v32, v70
	v_fmac_f32_e32 v2, v16, v70
	v_fmac_f32_e32 v86, v33, v70
	v_fmac_f32_e32 v3, v17, v70
	v_fmac_f32_e32 v84, v18, v70
	v_fmac_f32_e32 v83, v4, v70
	v_fmac_f32_e32 v82, v6, v70
	v_fmac_f32_e32 v81, v0, v70
	v_fmac_f32_e32 v80, v5, v70
	v_fmac_f32_e32 v79, v7, v70
	v_fmac_f32_e32 v78, v8, v70
	v_fmac_f32_e32 v77, v9, v70
	v_fma_f32 v70, v10, v70, v34
	v_fmac_f32_e32 v93, v15, v69
	v_fmac_f32_e32 v90, v31, v69
	v_fmac_f32_e32 v2, v32, v69
	v_fmac_f32_e32 v86, v16, v69
	v_fmac_f32_e32 v3, v33, v69
	v_fmac_f32_e32 v84, v17, v69
	v_fmac_f32_e32 v83, v18, v69
	v_fmac_f32_e32 v82, v4, v69
	v_fmac_f32_e32 v81, v6, v69
	v_fmac_f32_e32 v80, v0, v69
	v_fmac_f32_e32 v79, v5, v69
	v_fmac_f32_e32 v78, v7, v69
	v_fmac_f32_e32 v77, v8, v69
	v_fmac_f32_e32 v70, v9, v69
	v_fma_f32 v69, v10, v69, v34
	v_fmac_f32_e32 v93, v14, v64
	v_fmac_f32_e32 v90, v15, v64
	v_fmac_f32_e32 v2, v31, v64
	v_fmac_f32_e32 v86, v32, v64
	v_fmac_f32_e32 v3, v16, v64
	v_fmac_f32_e32 v84, v33, v64
	v_fmac_f32_e32 v83, v17, v64
	v_fmac_f32_e32 v82, v18, v64
	v_fmac_f32_e32 v81, v4, v64
	v_fmac_f32_e32 v80, v6, v64
	v_fmac_f32_e32 v79, v0, v64
	v_fmac_f32_e32 v78, v5, v64
	v_fmac_f32_e32 v77, v7, v64
	v_fmac_f32_e32 v70, v8, v64
	v_fmac_f32_e32 v69, v9, v64
	v_fma_f32 v64, v10, v64, v34
	v_fmac_f32_e32 v93, v12, v62
	v_fmac_f32_e32 v90, v14, v62
	v_fmac_f32_e32 v2, v15, v62
	v_fmac_f32_e32 v86, v31, v62
	v_fmac_f32_e32 v3, v32, v62
	v_fmac_f32_e32 v84, v16, v62
	v_fmac_f32_e32 v83, v33, v62
	v_fmac_f32_e32 v82, v17, v62
	v_fmac_f32_e32 v81, v18, v62
	v_fmac_f32_e32 v80, v4, v62
	v_fmac_f32_e32 v79, v6, v62
	v_fmac_f32_e32 v78, v0, v62
	v_fmac_f32_e32 v77, v5, v62
	v_fmac_f32_e32 v70, v7, v62
	v_fmac_f32_e32 v69, v8, v62
	v_fmac_f32_e32 v64, v9, v62
	v_fma_f32 v62, v10, v62, v34
	v_fmac_f32_e32 v93, v11, v55
	v_fmac_f32_e32 v90, v12, v55
	v_fmac_f32_e32 v2, v14, v55
	v_fmac_f32_e32 v86, v15, v55
	v_fmac_f32_e32 v3, v31, v55
	v_fmac_f32_e32 v84, v32, v55
	v_fmac_f32_e32 v83, v16, v55
	v_fmac_f32_e32 v82, v33, v55
	v_fmac_f32_e32 v81, v17, v55
	v_fmac_f32_e32 v80, v18, v55
	v_fmac_f32_e32 v79, v4, v55
	v_fmac_f32_e32 v78, v6, v55
	v_fmac_f32_e32 v77, v0, v55
	v_fmac_f32_e32 v70, v5, v55
	v_fmac_f32_e32 v69, v7, v55
	v_fmac_f32_e32 v64, v8, v55
	v_fmac_f32_e32 v62, v9, v55
; __device__ __forceinline__ void conv_item(LAS unsigned char* lds, const bf16* PROJ, bf16* MIX, const float* cw, const float* cb, const float* lg, const float* lb, int item, int tid) {
;     ...
;     float acc[32]; const float bias = cb[c];
; #pragma unroll
;     for (int tk = 0; tk < 32; ++tk) { float s = bias;
; #pragma unroll
;         for (int k = 0; k < 31; ++k) s += w[k] * hw[tk + k];
;         acc[tk] = s; }
	v_fma_f32 v55, v10, v55, v34
	v_fmac_f32_e32 v93, v13, v54
	v_fmac_f32_e32 v90, v11, v54
	v_fmac_f32_e32 v2, v12, v54
	v_fmac_f32_e32 v86, v14, v54
	v_fmac_f32_e32 v3, v15, v54
	v_fmac_f32_e32 v84, v31, v54
	v_fmac_f32_e32 v83, v32, v54
	v_fmac_f32_e32 v82, v16, v54
	v_fmac_f32_e32 v81, v33, v54
	v_fmac_f32_e32 v80, v17, v54
	v_fmac_f32_e32 v79, v18, v54
	v_fmac_f32_e32 v78, v4, v54
	v_fmac_f32_e32 v77, v6, v54
	v_fmac_f32_e32 v70, v0, v54
	v_fmac_f32_e32 v69, v5, v54
	v_fmac_f32_e32 v64, v7, v54
	v_fmac_f32_e32 v62, v8, v54
	v_fmac_f32_e32 v55, v9, v54
	v_fma_f32 v54, v10, v54, v34
	v_fmac_f32_e32 v93, v26, v52
	v_fmac_f32_e32 v90, v13, v52
	v_fmac_f32_e32 v2, v11, v52
	v_fmac_f32_e32 v86, v12, v52
	v_fmac_f32_e32 v3, v14, v52
	v_fmac_f32_e32 v84, v15, v52
	v_fmac_f32_e32 v83, v31, v52
	v_fmac_f32_e32 v82, v32, v52
	v_fmac_f32_e32 v81, v16, v52
	v_fmac_f32_e32 v80, v33, v52
	v_fmac_f32_e32 v79, v17, v52
	v_fmac_f32_e32 v78, v18, v52
	v_fmac_f32_e32 v77, v4, v52
	v_fmac_f32_e32 v70, v6, v52
	v_fmac_f32_e32 v69, v0, v52
	v_fmac_f32_e32 v64, v5, v52
	v_fmac_f32_e32 v62, v7, v52
	v_fmac_f32_e32 v55, v8, v52
	v_fmac_f32_e32 v54, v9, v52
	v_fma_f32 v52, v10, v52, v34
	v_fmac_f32_e32 v93, v30, v51
	v_fmac_f32_e32 v90, v26, v51
	v_fmac_f32_e32 v2, v13, v51
	v_fmac_f32_e32 v86, v11, v51
	v_fmac_f32_e32 v3, v12, v51
	v_fmac_f32_e32 v84, v14, v51
	v_fmac_f32_e32 v83, v15, v51
	v_fmac_f32_e32 v82, v31, v51
	v_fmac_f32_e32 v81, v32, v51
	v_fmac_f32_e32 v80, v16, v51
	v_fmac_f32_e32 v79, v33, v51
	v_fmac_f32_e32 v78, v17, v51
	v_fmac_f32_e32 v77, v18, v51
	v_fmac_f32_e32 v70, v4, v51
	v_fmac_f32_e32 v69, v6, v51
	v_fmac_f32_e32 v64, v0, v51
	v_fmac_f32_e32 v62, v5, v51
	v_fmac_f32_e32 v55, v7, v51
	v_fmac_f32_e32 v54, v8, v51
	v_fmac_f32_e32 v52, v9, v51
	v_fma_f32 v51, v10, v51, v34
	v_fmac_f32_e32 v93, v25, v50
	v_fmac_f32_e32 v90, v30, v50
	v_fmac_f32_e32 v2, v26, v50
	v_fmac_f32_e32 v86, v13, v50
	v_fmac_f32_e32 v3, v11, v50
	v_fmac_f32_e32 v84, v12, v50
	v_fmac_f32_e32 v83, v14, v50
	v_fmac_f32_e32 v82, v15, v50
	v_fmac_f32_e32 v81, v31, v50
	v_fmac_f32_e32 v80, v32, v50
	v_fmac_f32_e32 v79, v16, v50
	v_fmac_f32_e32 v78, v33, v50
	v_fmac_f32_e32 v77, v17, v50
	v_fmac_f32_e32 v70, v18, v50
	v_fmac_f32_e32 v69, v4, v50
	v_fmac_f32_e32 v64, v6, v50
	v_fmac_f32_e32 v62, v0, v50
	v_fmac_f32_e32 v55, v5, v50
	v_fmac_f32_e32 v54, v7, v50
	v_fmac_f32_e32 v52, v8, v50
	v_fmac_f32_e32 v51, v9, v50
	v_fma_f32 v50, v10, v50, v34
	v_fmac_f32_e32 v93, v29, v49
	v_fmac_f32_e32 v90, v25, v49
	v_fmac_f32_e32 v2, v30, v49
	v_fmac_f32_e32 v86, v26, v49
	v_fmac_f32_e32 v3, v13, v49
	v_fmac_f32_e32 v84, v11, v49
	v_fmac_f32_e32 v83, v12, v49
	v_fmac_f32_e32 v82, v14, v49
	v_fmac_f32_e32 v81, v15, v49
	v_fmac_f32_e32 v80, v31, v49
	v_fmac_f32_e32 v79, v32, v49
	v_fmac_f32_e32 v78, v16, v49
	v_fmac_f32_e32 v77, v33, v49
	v_fmac_f32_e32 v70, v17, v49
	v_fmac_f32_e32 v69, v18, v49
	v_fmac_f32_e32 v64, v4, v49
	v_fmac_f32_e32 v62, v6, v49
	v_fmac_f32_e32 v55, v0, v49
	v_fmac_f32_e32 v54, v5, v49
	v_fmac_f32_e32 v52, v7, v49
	v_fmac_f32_e32 v51, v8, v49
	v_fmac_f32_e32 v50, v9, v49
	v_fma_f32 v49, v10, v49, v34
	v_fmac_f32_e32 v93, v28, v46
	v_fmac_f32_e32 v90, v29, v46
	v_fmac_f32_e32 v2, v25, v46
	v_fmac_f32_e32 v86, v30, v46
	v_fmac_f32_e32 v3, v26, v46
	v_fmac_f32_e32 v84, v13, v46
	v_fmac_f32_e32 v83, v11, v46
	v_fmac_f32_e32 v82, v12, v46
	v_fmac_f32_e32 v81, v14, v46
	v_fmac_f32_e32 v80, v15, v46
	v_fmac_f32_e32 v79, v31, v46
	v_fmac_f32_e32 v78, v32, v46
	v_fmac_f32_e32 v77, v16, v46
	v_fmac_f32_e32 v70, v33, v46
	v_fmac_f32_e32 v69, v17, v46
	v_fmac_f32_e32 v64, v18, v46
	v_fmac_f32_e32 v62, v4, v46
	v_fmac_f32_e32 v55, v6, v46
	v_fmac_f32_e32 v54, v0, v46
	v_fmac_f32_e32 v52, v5, v46
	v_fmac_f32_e32 v51, v7, v46
	v_fmac_f32_e32 v50, v8, v46
	v_fmac_f32_e32 v49, v9, v46
	v_fma_f32 v46, v10, v46, v34
	v_fmac_f32_e32 v93, v24, v45
	v_fmac_f32_e32 v90, v28, v45
	v_fmac_f32_e32 v2, v29, v45
	v_fmac_f32_e32 v86, v25, v45
	v_fmac_f32_e32 v3, v30, v45
	v_fmac_f32_e32 v84, v26, v45
	v_fmac_f32_e32 v83, v13, v45
	v_fmac_f32_e32 v82, v11, v45
	v_fmac_f32_e32 v81, v12, v45
	v_fmac_f32_e32 v80, v14, v45
	v_fmac_f32_e32 v79, v15, v45
	v_fmac_f32_e32 v78, v31, v45
	v_fmac_f32_e32 v77, v32, v45
	v_fmac_f32_e32 v70, v16, v45
	v_fmac_f32_e32 v69, v33, v45
	v_fmac_f32_e32 v64, v17, v45
	v_fmac_f32_e32 v62, v18, v45
	v_fmac_f32_e32 v55, v4, v45
	v_fmac_f32_e32 v54, v6, v45
	v_fmac_f32_e32 v52, v0, v45
	v_fmac_f32_e32 v51, v5, v45
	v_fmac_f32_e32 v50, v7, v45
	v_fmac_f32_e32 v49, v8, v45
	v_fmac_f32_e32 v46, v9, v45
	v_fma_f32 v45, v10, v45, v34
	v_fmac_f32_e32 v93, v23, v44
	v_fmac_f32_e32 v90, v24, v44
	v_fmac_f32_e32 v2, v28, v44
	v_fmac_f32_e32 v86, v29, v44
	v_fmac_f32_e32 v3, v25, v44
	v_fmac_f32_e32 v84, v30, v44
	v_fmac_f32_e32 v83, v26, v44
	v_fmac_f32_e32 v82, v13, v44
	v_fmac_f32_e32 v81, v11, v44
	v_fmac_f32_e32 v80, v12, v44
	v_fmac_f32_e32 v79, v14, v44
	v_fmac_f32_e32 v78, v15, v44
	v_fmac_f32_e32 v77, v31, v44
	v_fmac_f32_e32 v70, v32, v44
	v_fmac_f32_e32 v69, v16, v44
	v_fmac_f32_e32 v64, v33, v44
	v_fmac_f32_e32 v62, v17, v44
	v_fmac_f32_e32 v55, v18, v44
	v_fmac_f32_e32 v54, v4, v44
	v_fmac_f32_e32 v52, v6, v44
	v_fmac_f32_e32 v51, v0, v44
	v_fmac_f32_e32 v50, v5, v44
	v_fmac_f32_e32 v49, v7, v44
	v_fmac_f32_e32 v46, v8, v44
	v_fmac_f32_e32 v45, v9, v44
	v_fma_f32 v44, v10, v44, v34
	v_fmac_f32_e32 v93, v21, v43
	v_fmac_f32_e32 v90, v23, v43
	v_fmac_f32_e32 v2, v24, v43
	v_fmac_f32_e32 v86, v28, v43
	v_fmac_f32_e32 v3, v29, v43
	v_fmac_f32_e32 v84, v25, v43
	v_fmac_f32_e32 v83, v30, v43
	v_fmac_f32_e32 v82, v26, v43
	v_fmac_f32_e32 v81, v13, v43
; __device__ __forceinline__ void conv_item(LAS unsigned char* lds, const bf16* PROJ, bf16* MIX, const float* cw, const float* cb, const float* lg, const float* lb, int item, int tid) {
;     ...
;     float acc[32]; const float bias = cb[c];
; #pragma unroll
;     for (int tk = 0; tk < 32; ++tk) { float s = bias;
; #pragma unroll
;         for (int k = 0; k < 31; ++k) s += w[k] * hw[tk + k];
;         acc[tk] = s; }
	v_fmac_f32_e32 v80, v11, v43
	v_fmac_f32_e32 v79, v12, v43
	v_fmac_f32_e32 v78, v14, v43
	v_fmac_f32_e32 v77, v15, v43
	v_fmac_f32_e32 v70, v31, v43
	v_fmac_f32_e32 v69, v32, v43
	v_fmac_f32_e32 v64, v16, v43
	v_fmac_f32_e32 v62, v33, v43
	v_fmac_f32_e32 v55, v17, v43
	v_fmac_f32_e32 v54, v18, v43
	v_fmac_f32_e32 v52, v4, v43
	v_fmac_f32_e32 v51, v6, v43
	v_fmac_f32_e32 v50, v0, v43
	v_fmac_f32_e32 v49, v5, v43
	v_fmac_f32_e32 v46, v7, v43
	v_fmac_f32_e32 v45, v8, v43
	v_fmac_f32_e32 v44, v9, v43
	v_fma_f32 v43, v10, v43, v34
	v_fmac_f32_e32 v93, v19, v40
	v_fmac_f32_e32 v90, v21, v40
	v_fmac_f32_e32 v2, v23, v40
	v_fmac_f32_e32 v86, v24, v40
	v_fmac_f32_e32 v3, v28, v40
	v_fmac_f32_e32 v84, v29, v40
	v_fmac_f32_e32 v83, v25, v40
	v_fmac_f32_e32 v82, v30, v40
	v_fmac_f32_e32 v81, v26, v40
	v_fmac_f32_e32 v80, v13, v40
	v_fmac_f32_e32 v79, v11, v40
	v_fmac_f32_e32 v78, v12, v40
	v_fmac_f32_e32 v77, v14, v40
	v_fmac_f32_e32 v70, v15, v40
	v_fmac_f32_e32 v69, v31, v40
	v_fmac_f32_e32 v64, v32, v40
	v_fmac_f32_e32 v62, v16, v40
	v_fmac_f32_e32 v55, v33, v40
	v_fmac_f32_e32 v54, v17, v40
	v_fmac_f32_e32 v52, v18, v40
	v_fmac_f32_e32 v51, v4, v40
	v_fmac_f32_e32 v50, v6, v40
	v_fmac_f32_e32 v49, v0, v40
	v_fmac_f32_e32 v46, v5, v40
	v_fmac_f32_e32 v45, v7, v40
	v_fmac_f32_e32 v44, v8, v40
	v_fmac_f32_e32 v43, v9, v40
	v_fma_f32 v40, v10, v40, v34
	v_fmac_f32_e32 v93, v22, v41
	v_fmac_f32_e32 v90, v19, v41
	v_fmac_f32_e32 v2, v21, v41
	v_fmac_f32_e32 v86, v23, v41
	v_fmac_f32_e32 v3, v24, v41
	v_fmac_f32_e32 v84, v28, v41
	v_fmac_f32_e32 v83, v29, v41
	v_fmac_f32_e32 v82, v25, v41
	v_fmac_f32_e32 v81, v30, v41
	v_fmac_f32_e32 v80, v26, v41
	v_fmac_f32_e32 v79, v13, v41
	v_fmac_f32_e32 v78, v11, v41
	v_fmac_f32_e32 v77, v12, v41
	v_fmac_f32_e32 v70, v14, v41
	v_fmac_f32_e32 v69, v15, v41
	v_fmac_f32_e32 v64, v31, v41
	v_fmac_f32_e32 v62, v32, v41
	v_fmac_f32_e32 v55, v16, v41
	v_fmac_f32_e32 v54, v33, v41
	v_fmac_f32_e32 v52, v17, v41
	v_fmac_f32_e32 v51, v18, v41
	v_fmac_f32_e32 v50, v4, v41
	v_fmac_f32_e32 v49, v6, v41
	v_fmac_f32_e32 v46, v0, v41
	v_fmac_f32_e32 v45, v5, v41
	v_fmac_f32_e32 v44, v7, v41
	v_fmac_f32_e32 v43, v8, v41
	v_fmac_f32_e32 v40, v9, v41
	v_fma_f32 v41, v10, v41, v34
	v_fmac_f32_e32 v93, v20, v38
	v_fmac_f32_e32 v90, v22, v38
	v_fmac_f32_e32 v2, v19, v38
	v_fmac_f32_e32 v86, v21, v38
	v_fmac_f32_e32 v3, v23, v38
	v_fmac_f32_e32 v84, v24, v38
	v_fmac_f32_e32 v83, v28, v38
	v_fmac_f32_e32 v82, v29, v38
	v_fmac_f32_e32 v81, v25, v38
	v_fmac_f32_e32 v80, v30, v38
	v_fmac_f32_e32 v79, v26, v38
	v_fmac_f32_e32 v78, v13, v38
	v_fmac_f32_e32 v77, v11, v38
	v_fmac_f32_e32 v70, v12, v38
	v_fmac_f32_e32 v69, v14, v38
	v_fmac_f32_e32 v64, v15, v38
	v_fmac_f32_e32 v62, v31, v38
	v_fmac_f32_e32 v55, v32, v38
	v_fmac_f32_e32 v54, v16, v38
	v_fmac_f32_e32 v52, v33, v38
	v_fmac_f32_e32 v51, v17, v38
	v_fmac_f32_e32 v50, v18, v38
	v_fmac_f32_e32 v49, v4, v38
	v_fmac_f32_e32 v46, v6, v38
	v_fmac_f32_e32 v45, v0, v38
	v_fmac_f32_e32 v44, v5, v38
	v_fmac_f32_e32 v43, v7, v38
	v_fmac_f32_e32 v40, v8, v38
	v_fmac_f32_e32 v41, v9, v38
	v_fma_f32 v38, v10, v38, v34
	v_fmac_f32_e32 v93, v27, v37
	v_fmac_f32_e32 v90, v20, v37
	v_fmac_f32_e32 v2, v22, v37
	v_fmac_f32_e32 v86, v19, v37
	v_fmac_f32_e32 v3, v21, v37
	v_fmac_f32_e32 v84, v23, v37
	v_fmac_f32_e32 v83, v24, v37
	v_fmac_f32_e32 v82, v28, v37
	v_fmac_f32_e32 v81, v29, v37
	v_fmac_f32_e32 v80, v25, v37
	v_fmac_f32_e32 v79, v30, v37
	v_fmac_f32_e32 v78, v26, v37
	v_fmac_f32_e32 v77, v13, v37
	v_fmac_f32_e32 v70, v11, v37
	v_fmac_f32_e32 v69, v12, v37
	v_fmac_f32_e32 v64, v14, v37
	v_fmac_f32_e32 v62, v15, v37
	v_fmac_f32_e32 v55, v31, v37
	v_fmac_f32_e32 v54, v32, v37
	v_fmac_f32_e32 v52, v16, v37
	v_fmac_f32_e32 v51, v33, v37
	v_fmac_f32_e32 v50, v17, v37
	v_fmac_f32_e32 v49, v18, v37
	v_fmac_f32_e32 v46, v4, v37
	v_fmac_f32_e32 v45, v6, v37
	v_fmac_f32_e32 v44, v0, v37
	v_fmac_f32_e32 v43, v5, v37
	v_fmac_f32_e32 v40, v7, v37
	v_fmac_f32_e32 v41, v8, v37
	v_fmac_f32_e32 v38, v9, v37
	v_fma_f32 v37, v10, v37, v34
	v_fmac_f32_e32 v34, v10, v36
	v_fmac_f32_e32 v37, v9, v36
	v_fmac_f32_e32 v34, v9, v39
	v_fmac_f32_e32 v38, v8, v36
	v_fmac_f32_e32 v37, v8, v39
	v_fmac_f32_e32 v34, v8, v42
	v_fmac_f32_e32 v41, v7, v36
	v_fmac_f32_e32 v38, v7, v39
	v_fmac_f32_e32 v37, v7, v42
	v_fmac_f32_e32 v34, v7, v47
	v_fmac_f32_e32 v40, v5, v36
	v_fmac_f32_e32 v41, v5, v39
	v_fmac_f32_e32 v38, v5, v42
	v_fmac_f32_e32 v37, v5, v47
	v_fmac_f32_e32 v34, v5, v48
	v_fmac_f32_e32 v43, v0, v36
	v_fmac_f32_e32 v40, v0, v39
	v_fmac_f32_e32 v41, v0, v42
	v_fmac_f32_e32 v38, v0, v47
	v_fmac_f32_e32 v37, v0, v48
	v_fmac_f32_e32 v34, v0, v53
	v_fmac_f32_e32 v44, v6, v36
	v_fmac_f32_e32 v43, v6, v39
	v_fmac_f32_e32 v40, v6, v42
	v_fmac_f32_e32 v41, v6, v47
	v_fmac_f32_e32 v38, v6, v48
	v_fmac_f32_e32 v37, v6, v53
	v_fmac_f32_e32 v34, v6, v56
	v_fmac_f32_e32 v45, v4, v36
	v_fmac_f32_e32 v44, v4, v39
	v_fmac_f32_e32 v43, v4, v42
	v_fmac_f32_e32 v40, v4, v47
	v_fmac_f32_e32 v41, v4, v48
	v_fmac_f32_e32 v38, v4, v53
	v_fmac_f32_e32 v37, v4, v56
	v_fmac_f32_e32 v34, v4, v57
	v_fmac_f32_e32 v46, v18, v36
	v_fmac_f32_e32 v45, v18, v39
	v_fmac_f32_e32 v44, v18, v42
	v_fmac_f32_e32 v43, v18, v47
	v_fmac_f32_e32 v40, v18, v48
	v_fmac_f32_e32 v41, v18, v53
	v_fmac_f32_e32 v38, v18, v56
	v_fmac_f32_e32 v37, v18, v57
	v_fmac_f32_e32 v34, v18, v58
	v_fmac_f32_e32 v49, v17, v36
	v_fmac_f32_e32 v46, v17, v39
	v_fmac_f32_e32 v45, v17, v42
	v_fmac_f32_e32 v44, v17, v47
	v_fmac_f32_e32 v43, v17, v48
	v_fmac_f32_e32 v40, v17, v53
	v_fmac_f32_e32 v41, v17, v56
	v_fmac_f32_e32 v38, v17, v57
	v_fmac_f32_e32 v37, v17, v58
	v_fmac_f32_e32 v34, v17, v59
; __device__ __forceinline__ void conv_item(LAS unsigned char* lds, const bf16* PROJ, bf16* MIX, const float* cw, const float* cb, const float* lg, const float* lb, int item, int tid) {
;     ...
;     float acc[32]; const float bias = cb[c];
; #pragma unroll
;     for (int tk = 0; tk < 32; ++tk) { float s = bias;
; #pragma unroll
;         for (int k = 0; k < 31; ++k) s += w[k] * hw[tk + k];
;         acc[tk] = s; }
	v_fmac_f32_e32 v50, v33, v36
	v_fmac_f32_e32 v49, v33, v39
	v_fmac_f32_e32 v46, v33, v42
	v_fmac_f32_e32 v45, v33, v47
	v_fmac_f32_e32 v44, v33, v48
	v_fmac_f32_e32 v43, v33, v53
	v_fmac_f32_e32 v40, v33, v56
	v_fmac_f32_e32 v41, v33, v57
	v_fmac_f32_e32 v38, v33, v58
	v_fmac_f32_e32 v37, v33, v59
	v_fmac_f32_e32 v34, v33, v60
	v_fmac_f32_e32 v51, v16, v36
	v_fmac_f32_e32 v50, v16, v39
	v_fmac_f32_e32 v49, v16, v42
	v_fmac_f32_e32 v46, v16, v47
	v_fmac_f32_e32 v45, v16, v48
	v_fmac_f32_e32 v44, v16, v53
	v_fmac_f32_e32 v43, v16, v56
	v_fmac_f32_e32 v40, v16, v57
	v_fmac_f32_e32 v41, v16, v58
	v_fmac_f32_e32 v38, v16, v59
	v_fmac_f32_e32 v37, v16, v60
	v_fmac_f32_e32 v34, v16, v61
	v_fmac_f32_e32 v52, v32, v36
	v_fmac_f32_e32 v51, v32, v39
	v_fmac_f32_e32 v50, v32, v42
	v_fmac_f32_e32 v49, v32, v47
	v_fmac_f32_e32 v46, v32, v48
	v_fmac_f32_e32 v45, v32, v53
	v_fmac_f32_e32 v44, v32, v56
	v_fmac_f32_e32 v43, v32, v57
	v_fmac_f32_e32 v40, v32, v58
	v_fmac_f32_e32 v41, v32, v59
	v_fmac_f32_e32 v38, v32, v60
	v_fmac_f32_e32 v37, v32, v61
	v_fmac_f32_e32 v34, v32, v63
	v_fmac_f32_e32 v54, v31, v36
	v_fmac_f32_e32 v52, v31, v39
	v_fmac_f32_e32 v51, v31, v42
	v_fmac_f32_e32 v50, v31, v47
	v_fmac_f32_e32 v49, v31, v48
	v_fmac_f32_e32 v46, v31, v53
	v_fmac_f32_e32 v45, v31, v56
	v_fmac_f32_e32 v44, v31, v57
	v_fmac_f32_e32 v43, v31, v58
	v_fmac_f32_e32 v40, v31, v59
	v_fmac_f32_e32 v41, v31, v60
	v_fmac_f32_e32 v38, v31, v61
	v_fmac_f32_e32 v37, v31, v63
	v_fmac_f32_e32 v34, v31, v65
	v_fmac_f32_e32 v55, v15, v36
	v_fmac_f32_e32 v54, v15, v39
	v_fmac_f32_e32 v52, v15, v42
	v_fmac_f32_e32 v51, v15, v47
	v_fmac_f32_e32 v50, v15, v48
	v_fmac_f32_e32 v49, v15, v53
	v_fmac_f32_e32 v46, v15, v56
	v_fmac_f32_e32 v45, v15, v57
	v_fmac_f32_e32 v44, v15, v58
	v_fmac_f32_e32 v43, v15, v59
	v_fmac_f32_e32 v40, v15, v60
	v_fmac_f32_e32 v41, v15, v61
	v_fmac_f32_e32 v38, v15, v63
	v_fmac_f32_e32 v37, v15, v65
	v_fmac_f32_e32 v34, v15, v66
	v_fmac_f32_e32 v62, v14, v36
	v_fmac_f32_e32 v55, v14, v39
	v_fmac_f32_e32 v54, v14, v42
	v_fmac_f32_e32 v52, v14, v47
	v_fmac_f32_e32 v51, v14, v48
	v_fmac_f32_e32 v50, v14, v53
	v_fmac_f32_e32 v49, v14, v56
	v_fmac_f32_e32 v46, v14, v57
	v_fmac_f32_e32 v45, v14, v58
	v_fmac_f32_e32 v44, v14, v59
	v_fmac_f32_e32 v43, v14, v60
	v_fmac_f32_e32 v40, v14, v61
	v_fmac_f32_e32 v41, v14, v63
	v_fmac_f32_e32 v38, v14, v65
	v_fmac_f32_e32 v37, v14, v66
	v_fmac_f32_e32 v34, v14, v67
	v_fmac_f32_e32 v64, v12, v36
	v_fmac_f32_e32 v62, v12, v39
	v_fmac_f32_e32 v55, v12, v42
	v_fmac_f32_e32 v54, v12, v47
	v_fmac_f32_e32 v52, v12, v48
	v_fmac_f32_e32 v51, v12, v53
	v_fmac_f32_e32 v50, v12, v56
	v_fmac_f32_e32 v49, v12, v57
	v_fmac_f32_e32 v46, v12, v58
	v_fmac_f32_e32 v45, v12, v59
	v_fmac_f32_e32 v44, v12, v60
	v_fmac_f32_e32 v43, v12, v61
	v_fmac_f32_e32 v40, v12, v63
	v_fmac_f32_e32 v41, v12, v65
	v_fmac_f32_e32 v38, v12, v66
	v_fmac_f32_e32 v37, v12, v67
	v_fmac_f32_e32 v34, v12, v68
	v_fmac_f32_e32 v69, v11, v36
	v_fmac_f32_e32 v64, v11, v39
	v_fmac_f32_e32 v62, v11, v42
	v_fmac_f32_e32 v55, v11, v47
	v_fmac_f32_e32 v54, v11, v48
	v_fmac_f32_e32 v52, v11, v53
	v_fmac_f32_e32 v51, v11, v56
	v_fmac_f32_e32 v50, v11, v57
	v_fmac_f32_e32 v49, v11, v58
	v_fmac_f32_e32 v46, v11, v59
	v_fmac_f32_e32 v45, v11, v60
	v_fmac_f32_e32 v44, v11, v61
	v_fmac_f32_e32 v43, v11, v63
	v_fmac_f32_e32 v40, v11, v65
	v_fmac_f32_e32 v41, v11, v66
	v_fmac_f32_e32 v38, v11, v67
	v_fmac_f32_e32 v37, v11, v68
	v_fmac_f32_e32 v34, v11, v71
	v_fmac_f32_e32 v70, v13, v36
	v_fmac_f32_e32 v69, v13, v39
	v_fmac_f32_e32 v64, v13, v42
	v_fmac_f32_e32 v62, v13, v47
	v_fmac_f32_e32 v55, v13, v48
	v_fmac_f32_e32 v54, v13, v53
	v_fmac_f32_e32 v52, v13, v56
	v_fmac_f32_e32 v51, v13, v57
	v_fmac_f32_e32 v50, v13, v58
	v_fmac_f32_e32 v49, v13, v59
	v_fmac_f32_e32 v46, v13, v60
	v_fmac_f32_e32 v45, v13, v61
	v_fmac_f32_e32 v44, v13, v63
	v_fmac_f32_e32 v43, v13, v65
	v_fmac_f32_e32 v40, v13, v66
	v_fmac_f32_e32 v41, v13, v67
	v_fmac_f32_e32 v38, v13, v68
	v_fmac_f32_e32 v37, v13, v71
	v_fmac_f32_e32 v34, v13, v72
	v_fmac_f32_e32 v77, v26, v36
	v_fmac_f32_e32 v70, v26, v39
	v_fmac_f32_e32 v69, v26, v42
	v_fmac_f32_e32 v64, v26, v47
	v_fmac_f32_e32 v62, v26, v48
	v_fmac_f32_e32 v55, v26, v53
	v_fmac_f32_e32 v54, v26, v56
	v_fmac_f32_e32 v52, v26, v57
	v_fmac_f32_e32 v51, v26, v58
	v_fmac_f32_e32 v50, v26, v59
	v_fmac_f32_e32 v49, v26, v60
	v_fmac_f32_e32 v46, v26, v61
	v_fmac_f32_e32 v45, v26, v63
	v_fmac_f32_e32 v44, v26, v65
	v_fmac_f32_e32 v43, v26, v66
	v_fmac_f32_e32 v40, v26, v67
	v_fmac_f32_e32 v41, v26, v68
	v_fmac_f32_e32 v38, v26, v71
	v_fmac_f32_e32 v37, v26, v72
	v_fmac_f32_e32 v34, v26, v73
	v_fmac_f32_e32 v78, v30, v36
	v_fmac_f32_e32 v77, v30, v39
	v_fmac_f32_e32 v70, v30, v42
	v_fmac_f32_e32 v69, v30, v47
	v_fmac_f32_e32 v64, v30, v48
	v_fmac_f32_e32 v62, v30, v53
	v_fmac_f32_e32 v55, v30, v56
	v_fmac_f32_e32 v54, v30, v57
	v_fmac_f32_e32 v52, v30, v58
	v_fmac_f32_e32 v51, v30, v59
	v_fmac_f32_e32 v50, v30, v60
	v_fmac_f32_e32 v49, v30, v61
	v_fmac_f32_e32 v46, v30, v63
	v_fmac_f32_e32 v45, v30, v65
	v_fmac_f32_e32 v44, v30, v66
	v_fmac_f32_e32 v43, v30, v67
	v_fmac_f32_e32 v40, v30, v68
	v_fmac_f32_e32 v41, v30, v71
	v_fmac_f32_e32 v38, v30, v72
	v_fmac_f32_e32 v37, v30, v73
	v_fmac_f32_e32 v34, v30, v74
	v_fmac_f32_e32 v79, v25, v36
	v_fmac_f32_e32 v78, v25, v39
	v_fmac_f32_e32 v77, v25, v42
	v_fmac_f32_e32 v70, v25, v47
	v_fmac_f32_e32 v69, v25, v48
	v_fmac_f32_e32 v64, v25, v53
	v_fmac_f32_e32 v62, v25, v56
	v_fmac_f32_e32 v55, v25, v57
	v_fmac_f32_e32 v54, v25, v58
	v_fmac_f32_e32 v52, v25, v59
	v_fmac_f32_e32 v51, v25, v60
	v_fmac_f32_e32 v50, v25, v61
; __device__ __forceinline__ void conv_item(LAS unsigned char* lds, const bf16* PROJ, bf16* MIX, const float* cw, const float* cb, const float* lg, const float* lb, int item, int tid) {
;     ...
;     float acc[32]; const float bias = cb[c];
; #pragma unroll
;     for (int tk = 0; tk < 32; ++tk) { float s = bias;
; #pragma unroll
;         for (int k = 0; k < 31; ++k) s += w[k] * hw[tk + k];
;         acc[tk] = s; }
	v_fmac_f32_e32 v49, v25, v63
	v_fmac_f32_e32 v46, v25, v65
	v_fmac_f32_e32 v45, v25, v66
	v_fmac_f32_e32 v44, v25, v67
	v_fmac_f32_e32 v43, v25, v68
	v_fmac_f32_e32 v40, v25, v71
	v_fmac_f32_e32 v41, v25, v72
	v_fmac_f32_e32 v38, v25, v73
	v_fmac_f32_e32 v37, v25, v74
	v_fmac_f32_e32 v34, v25, v75
	v_fmac_f32_e32 v80, v29, v36
	v_fmac_f32_e32 v79, v29, v39
	v_fmac_f32_e32 v78, v29, v42
	v_fmac_f32_e32 v77, v29, v47
	v_fmac_f32_e32 v70, v29, v48
	v_fmac_f32_e32 v69, v29, v53
	v_fmac_f32_e32 v64, v29, v56
	v_fmac_f32_e32 v62, v29, v57
	v_fmac_f32_e32 v55, v29, v58
	v_fmac_f32_e32 v54, v29, v59
	v_fmac_f32_e32 v52, v29, v60
	v_fmac_f32_e32 v51, v29, v61
	v_fmac_f32_e32 v50, v29, v63
	v_fmac_f32_e32 v49, v29, v65
	v_fmac_f32_e32 v46, v29, v66
	v_fmac_f32_e32 v45, v29, v67
	v_fmac_f32_e32 v44, v29, v68
	v_fmac_f32_e32 v43, v29, v71
	v_fmac_f32_e32 v40, v29, v72
	v_fmac_f32_e32 v41, v29, v73
	v_fmac_f32_e32 v38, v29, v74
	v_fmac_f32_e32 v37, v29, v75
	v_fmac_f32_e32 v34, v29, v76
	v_fmac_f32_e32 v81, v28, v36
	v_fmac_f32_e32 v80, v28, v39
	v_fmac_f32_e32 v79, v28, v42
	v_fmac_f32_e32 v78, v28, v47
	v_fmac_f32_e32 v77, v28, v48
	v_fmac_f32_e32 v70, v28, v53
	v_fmac_f32_e32 v69, v28, v56
	v_fmac_f32_e32 v64, v28, v57
	v_fmac_f32_e32 v62, v28, v58
	v_fmac_f32_e32 v55, v28, v59
	v_fmac_f32_e32 v54, v28, v60
	v_fmac_f32_e32 v52, v28, v61
	v_fmac_f32_e32 v51, v28, v63
	v_fmac_f32_e32 v50, v28, v65
	v_fmac_f32_e32 v49, v28, v66
	v_fmac_f32_e32 v46, v28, v67
	v_fmac_f32_e32 v45, v28, v68
	v_fmac_f32_e32 v44, v28, v71
	v_fmac_f32_e32 v43, v28, v72
	v_fmac_f32_e32 v40, v28, v73
	v_fmac_f32_e32 v41, v28, v74
	v_fmac_f32_e32 v38, v28, v75
	v_fmac_f32_e32 v37, v28, v76
	v_fmac_f32_e32 v34, v28, v87
	v_fmac_f32_e32 v82, v24, v36
	v_fmac_f32_e32 v81, v24, v39
	v_fmac_f32_e32 v80, v24, v42
	v_fmac_f32_e32 v79, v24, v47
	v_fmac_f32_e32 v78, v24, v48
	v_fmac_f32_e32 v77, v24, v53
	v_fmac_f32_e32 v70, v24, v56
	v_fmac_f32_e32 v69, v24, v57
	v_fmac_f32_e32 v64, v24, v58
	v_fmac_f32_e32 v62, v24, v59
	v_fmac_f32_e32 v55, v24, v60
	v_fmac_f32_e32 v54, v24, v61
	v_fmac_f32_e32 v52, v24, v63
	v_fmac_f32_e32 v51, v24, v65
	v_fmac_f32_e32 v50, v24, v66
	v_fmac_f32_e32 v49, v24, v67
	v_fmac_f32_e32 v46, v24, v68
	v_fmac_f32_e32 v45, v24, v71
	v_fmac_f32_e32 v44, v24, v72
	v_fmac_f32_e32 v43, v24, v73
	v_fmac_f32_e32 v40, v24, v74
	v_fmac_f32_e32 v41, v24, v75
	v_fmac_f32_e32 v38, v24, v76
	v_fmac_f32_e32 v37, v24, v87
	v_fmac_f32_e32 v34, v24, v88
	v_fmac_f32_e32 v83, v23, v36
	v_fmac_f32_e32 v82, v23, v39
	v_fmac_f32_e32 v81, v23, v42
	v_fmac_f32_e32 v80, v23, v47
	v_fmac_f32_e32 v79, v23, v48
	v_fmac_f32_e32 v78, v23, v53
	v_fmac_f32_e32 v77, v23, v56
	v_fmac_f32_e32 v70, v23, v57
	v_fmac_f32_e32 v69, v23, v58
	v_fmac_f32_e32 v64, v23, v59
	v_fmac_f32_e32 v62, v23, v60
	v_fmac_f32_e32 v55, v23, v61
	v_fmac_f32_e32 v54, v23, v63
	v_fmac_f32_e32 v52, v23, v65
	v_fmac_f32_e32 v51, v23, v66
	v_fmac_f32_e32 v50, v23, v67
	v_fmac_f32_e32 v49, v23, v68
	v_fmac_f32_e32 v46, v23, v71
	v_fmac_f32_e32 v45, v23, v72
	v_fmac_f32_e32 v44, v23, v73
	v_fmac_f32_e32 v43, v23, v74
	v_fmac_f32_e32 v40, v23, v75
	v_fmac_f32_e32 v41, v23, v76
	v_fmac_f32_e32 v38, v23, v87
	v_fmac_f32_e32 v37, v23, v88
	v_fmac_f32_e32 v34, v23, v89
	v_fmac_f32_e32 v84, v21, v36
	v_fmac_f32_e32 v83, v21, v39
	v_fmac_f32_e32 v82, v21, v42
	v_fmac_f32_e32 v81, v21, v47
	v_fmac_f32_e32 v80, v21, v48
	v_fmac_f32_e32 v79, v21, v53
	v_fmac_f32_e32 v78, v21, v56
	v_fmac_f32_e32 v77, v21, v57
	v_fmac_f32_e32 v70, v21, v58
	v_fmac_f32_e32 v69, v21, v59
	v_fmac_f32_e32 v64, v21, v60
	v_fmac_f32_e32 v62, v21, v61
	v_fmac_f32_e32 v55, v21, v63
	v_fmac_f32_e32 v54, v21, v65
	v_fmac_f32_e32 v52, v21, v66
	v_fmac_f32_e32 v51, v21, v67
	v_fmac_f32_e32 v50, v21, v68
	v_fmac_f32_e32 v49, v21, v71
	v_fmac_f32_e32 v46, v21, v72
	v_fmac_f32_e32 v45, v21, v73
	v_fmac_f32_e32 v44, v21, v74
	v_fmac_f32_e32 v43, v21, v75
	v_fmac_f32_e32 v40, v21, v76
	v_fmac_f32_e32 v41, v21, v87
	v_fmac_f32_e32 v38, v21, v88
	v_fmac_f32_e32 v37, v21, v89
	v_fmac_f32_e32 v34, v21, v92
	v_fmac_f32_e32 v3, v19, v36
	v_fmac_f32_e32 v84, v19, v39
	v_fmac_f32_e32 v83, v19, v42
	v_fmac_f32_e32 v82, v19, v47
	v_fmac_f32_e32 v81, v19, v48
	v_fmac_f32_e32 v80, v19, v53
	v_fmac_f32_e32 v79, v19, v56
	v_fmac_f32_e32 v78, v19, v57
	v_fmac_f32_e32 v77, v19, v58
	v_fmac_f32_e32 v70, v19, v59
	v_fmac_f32_e32 v69, v19, v60
	v_fmac_f32_e32 v64, v19, v61
	v_fmac_f32_e32 v62, v19, v63
	v_fmac_f32_e32 v55, v19, v65
	v_fmac_f32_e32 v54, v19, v66
	v_fmac_f32_e32 v52, v19, v67
	v_fmac_f32_e32 v51, v19, v68
	v_fmac_f32_e32 v50, v19, v71
	v_fmac_f32_e32 v49, v19, v72
	v_fmac_f32_e32 v46, v19, v73
	v_fmac_f32_e32 v45, v19, v74
	v_fmac_f32_e32 v44, v19, v75
	v_fmac_f32_e32 v43, v19, v76
	v_fmac_f32_e32 v40, v19, v87
	v_fmac_f32_e32 v41, v19, v88
	v_fmac_f32_e32 v38, v19, v89
	v_fmac_f32_e32 v37, v19, v92
	v_fmac_f32_e32 v34, v19, v94
	v_fmac_f32_e32 v86, v22, v36
	v_fmac_f32_e32 v3, v22, v39
	v_fmac_f32_e32 v84, v22, v42
	v_fmac_f32_e32 v83, v22, v47
	v_fmac_f32_e32 v82, v22, v48
	v_fmac_f32_e32 v81, v22, v53
	v_fmac_f32_e32 v80, v22, v56
	v_fmac_f32_e32 v79, v22, v57
	v_fmac_f32_e32 v78, v22, v58
	v_fmac_f32_e32 v77, v22, v59
	v_fmac_f32_e32 v70, v22, v60
	v_fmac_f32_e32 v69, v22, v61
	v_fmac_f32_e32 v64, v22, v63
	v_fmac_f32_e32 v62, v22, v65
	v_fmac_f32_e32 v55, v22, v66
	v_fmac_f32_e32 v54, v22, v67
	v_fmac_f32_e32 v52, v22, v68
	v_fmac_f32_e32 v51, v22, v71
	v_fmac_f32_e32 v50, v22, v72
	v_fmac_f32_e32 v49, v22, v73
	v_fmac_f32_e32 v46, v22, v74
	v_fmac_f32_e32 v45, v22, v75
	v_fmac_f32_e32 v44, v22, v76
	v_fmac_f32_e32 v43, v22, v87
	v_fmac_f32_e32 v40, v22, v88
; #define LAS __attribute__((address_space(3)))
; __device__ __forceinline__ void conv_item(LAS unsigned char* lds, const bf16* PROJ, bf16* MIX, const float* cw, const float* cb, const float* lg, const float* lb, int item, int tid) {
;     ...
;     LAS float* cbuf = (LAS float*)lds; LAS float* st = (LAS float*)(lds + 32 * 512 * 4);
; #pragma unroll
;     for (int tk = 0; tk < 32; ++tk) cbuf[tk * 512 + c] = acc[tk];
;     __syncthreads();
; #pragma unroll
;     for (int q = 0; q < 4; ++q) { const int tk = 4 * wid + q; float v[8]; float s = 0.f;
; #pragma unroll
;         for (int i = 0; i < 8; ++i) { v[i] = cbuf[tk * 512 + lane + 64 * i]; s += v[i]; }
;         const float mean = wave_sum(s, lane) * (1.f / 512.f); float s2 = 0.f;
; #pragma unroll
;         for (int i = 0; i < 8; ++i) { const float d = v[i] - mean; s2 += d * d; }
;         const float rstd = 1.0f / sqrtf(wave_sum(s2, lane) * (1.f / 512.f) + 1e-5f);
;         if (lane == 0) { st[2 * tk] = mean; st[2 * tk + 1] = rstd; } }
	v_fmac_f32_e32 v41, v22, v89
	v_fmac_f32_e32 v38, v22, v92
	v_fmac_f32_e32 v37, v22, v94
	v_fmac_f32_e32 v34, v22, v95
	v_fmac_f32_e32 v90, v27, v36
	v_fmac_f32_e32 v2, v20, v36
	v_fmac_f32_e32 v86, v20, v39
	v_fmac_f32_e32 v3, v20, v42
	v_fmac_f32_e32 v84, v20, v47
	v_fmac_f32_e32 v83, v20, v48
	v_fmac_f32_e32 v82, v20, v53
	v_fmac_f32_e32 v81, v20, v56
	v_fmac_f32_e32 v80, v20, v57
	v_fmac_f32_e32 v79, v20, v58
	v_fmac_f32_e32 v78, v20, v59
	v_fmac_f32_e32 v77, v20, v60
	v_fmac_f32_e32 v70, v20, v61
	v_fmac_f32_e32 v69, v20, v63
	v_fmac_f32_e32 v64, v20, v65
	v_fmac_f32_e32 v62, v20, v66
	v_fmac_f32_e32 v55, v20, v67
	v_fmac_f32_e32 v54, v20, v68
	v_fmac_f32_e32 v52, v20, v71
	v_fmac_f32_e32 v51, v20, v72
	v_fmac_f32_e32 v50, v20, v73
	v_fmac_f32_e32 v49, v20, v74
	v_fmac_f32_e32 v46, v20, v75
	v_fmac_f32_e32 v45, v20, v76
	v_fmac_f32_e32 v44, v20, v87
	v_fmac_f32_e32 v43, v20, v88
	v_fmac_f32_e32 v40, v20, v89
	v_fmac_f32_e32 v41, v20, v92
	v_fmac_f32_e32 v38, v20, v94
	v_fmac_f32_e32 v37, v20, v95
	v_fmac_f32_e32 v34, v20, v96
	v_lshl_add_u32 v0, v200, 2, 0
	v_fmac_f32_e32 v2, v27, v39
	v_fmac_f32_e32 v86, v27, v42
	v_fmac_f32_e32 v3, v27, v47
	v_fmac_f32_e32 v84, v27, v48
	v_fmac_f32_e32 v83, v27, v53
	v_fmac_f32_e32 v82, v27, v56
	v_fmac_f32_e32 v81, v27, v57
	v_fmac_f32_e32 v80, v27, v58
	v_fmac_f32_e32 v79, v27, v59
	v_fmac_f32_e32 v78, v27, v60
	v_fmac_f32_e32 v77, v27, v61
	v_fmac_f32_e32 v70, v27, v63
	v_fmac_f32_e32 v69, v27, v65
	v_fmac_f32_e32 v64, v27, v66
	v_fmac_f32_e32 v62, v27, v67
	v_fmac_f32_e32 v55, v27, v68
	v_fmac_f32_e32 v54, v27, v71
	v_fmac_f32_e32 v52, v27, v72
	v_fmac_f32_e32 v51, v27, v73
	v_fmac_f32_e32 v50, v27, v74
	v_fmac_f32_e32 v49, v27, v75
	v_fmac_f32_e32 v46, v27, v76
	v_fmac_f32_e32 v45, v27, v87
	v_fmac_f32_e32 v44, v27, v88
	v_fmac_f32_e32 v43, v27, v89
	v_fmac_f32_e32 v40, v27, v92
	v_fmac_f32_e32 v41, v27, v94
	v_fmac_f32_e32 v38, v27, v95
	v_fmac_f32_e32 v37, v27, v96
	v_fmac_f32_e32 v34, v27, v97
	ds_write2st64_b32 v0, v93, v90 offset1:8
	ds_write2st64_b32 v0, v2, v86 offset0:16 offset1:24
	ds_write2st64_b32 v0, v3, v84 offset0:32 offset1:40
	ds_write2st64_b32 v0, v83, v82 offset0:48 offset1:56
	ds_write2st64_b32 v0, v81, v80 offset0:64 offset1:72
	ds_write2st64_b32 v0, v79, v78 offset0:80 offset1:88
	ds_write2st64_b32 v0, v77, v70 offset0:96 offset1:104
	ds_write2st64_b32 v0, v69, v64 offset0:112 offset1:120
	ds_write2st64_b32 v0, v62, v55 offset0:128 offset1:136
	ds_write2st64_b32 v0, v54, v52 offset0:144 offset1:152
	ds_write2st64_b32 v0, v51, v50 offset0:160 offset1:168
	ds_write2st64_b32 v0, v49, v46 offset0:176 offset1:184
	ds_write2st64_b32 v0, v45, v44 offset0:192 offset1:200
	ds_write2st64_b32 v0, v43, v40 offset0:208 offset1:216
	ds_write2st64_b32 v0, v41, v38 offset0:224 offset1:232
	ds_write2st64_b32 v0, v37, v34 offset0:240 offset1:248
	v_lshlrev_b32_e32 v0, 2, v35
	v_add_u32_e32 v9, 0, v0
	v_lshl_add_u32 v10, s4, 11, v9
	s_waitcnt lgkmcnt(0)
	s_barrier
	ds_read2st64_b32 v[12:13], v10 offset1:1
	ds_read2st64_b32 v[14:15], v10 offset0:2 offset1:3
	ds_read2st64_b32 v[16:17], v10 offset0:4 offset1:5
	ds_read2st64_b32 v[18:19], v10 offset0:6 offset1:7
	v_xor_b32_e32 v8, 4, v0
	s_waitcnt lgkmcnt(3)
	v_add_f32_e32 v11, 0, v12
	v_add_f32_e32 v11, v11, v13
	s_waitcnt lgkmcnt(2)
	v_add_f32_e32 v11, v11, v14
	v_add_f32_e32 v11, v11, v15
	s_waitcnt lgkmcnt(1)
	v_add_f32_e32 v11, v11, v16
	v_add_f32_e32 v11, v11, v17
	s_waitcnt lgkmcnt(0)
	v_add_f32_e32 v10, v11, v18
	v_add_f32_e32 v10, v10, v19
	v_xor_b32_e32 v7, 8, v0
	v_xor_b32_e32 v6, 16, v0
	v_xor_b32_e32 v5, 32, v0
	v_xor_b32_e32 v4, 64, v0
	s_nop 1
	v_add_f32_dpp v10, v10, v10 quad_perm:[1,0,3,2] row_mask:0xf bank_mask:0xf
	v_xor_b32_e32 v0, 0x80, v0
	s_nop 1
	v_add_f32_dpp v10, v10, v10 quad_perm:[2,3,0,1] row_mask:0xf bank_mask:0xf
	s_nop 1
	v_add_f32_dpp v10, v10, v10 row_half_mirror row_mask:0xf bank_mask:0xf
	s_nop 1
	v_add_f32_dpp v10, v10, v10 row_mirror row_mask:0xf bank_mask:0xf
	ds_bpermute_b32 v11, v4, v10
	s_waitcnt lgkmcnt(0)
	v_add_f32_e32 v10, v10, v11
	ds_bpermute_b32 v11, v0, v10
	s_waitcnt lgkmcnt(0)
	v_add_f32_e32 v10, v10, v11
	v_fmac_f32_e32 v13, 0xbb000000, v10
	v_fmamk_f32 v11, v10, 0xbb000000, v12
	v_mul_f32_e32 v12, v13, v13
	v_fmac_f32_e32 v12, v11, v11
	v_fmamk_f32 v11, v10, 0xbb000000, v14
	v_fmac_f32_e32 v12, v11, v11
	v_fmac_f32_e32 v15, 0xbb000000, v10
	v_fmac_f32_e32 v12, v15, v15
	v_fmamk_f32 v11, v10, 0xbb000000, v16
	v_fmac_f32_e32 v12, v11, v11
	v_fmac_f32_e32 v17, 0xbb000000, v10
	v_fmac_f32_e32 v12, v17, v17
	v_fmamk_f32 v11, v10, 0xbb000000, v18
	v_fmac_f32_e32 v12, v11, v11
	v_fmac_f32_e32 v19, 0xbb000000, v10
	v_fmac_f32_e32 v12, v19, v19
	s_nop 1
	v_add_f32_dpp v11, v12, v12 quad_perm:[1,0,3,2] row_mask:0xf bank_mask:0xf
	s_nop 1
	v_add_f32_dpp v11, v11, v11 quad_perm:[2,3,0,1] row_mask:0xf bank_mask:0xf
	s_nop 1
	v_add_f32_dpp v11, v11, v11 row_half_mirror row_mask:0xf bank_mask:0xf
	s_nop 1
	v_add_f32_dpp v11, v11, v11 row_mirror row_mask:0xf bank_mask:0xf
	ds_bpermute_b32 v12, v4, v11
	s_waitcnt lgkmcnt(0)
	v_add_f32_e32 v11, v11, v12
	ds_bpermute_b32 v12, v0, v11
	s_and_saveexec_b64 s[0:1], s[8:9]
	s_cbranch_execz .LBB0_434
	s_waitcnt lgkmcnt(0)
	v_add_f32_e32 v11, v11, v12
	v_fmamk_f32 v11, v11, 0x3b000000, v232
	v_mul_f32_e32 v12, 0x4f800000, v11
	v_cmp_gt_f32_e32 vcc, s80, v11
	s_lshl_b32 s5, s4, 3
	s_add_i32 s5, s5, 0
	v_cndmask_b32_e32 v11, v11, v12, vcc
	v_sqrt_f32_e32 v12, v11
	s_add_i32 s5, s5, 0x10000
	v_mul_f32_e32 v10, 0x3b000000, v10
	v_add_u32_e32 v13, -1, v12
	v_fma_f32 v15, -v13, v12, v11
	v_add_u32_e32 v14, 1, v12
	v_cmp_ge_f32_e64 s[10:11], 0, v15
	s_nop 1
	v_cndmask_b32_e64 v13, v12, v13, s[10:11]
	v_fma_f32 v12, -v14, v12, v11
	v_cmp_lt_f32_e64 s[10:11], 0, v12
	s_nop 1
	v_cndmask_b32_e64 v12, v13, v14, s[10:11]
	v_mul_f32_e32 v13, 0x37800000, v12
	v_cndmask_b32_e32 v12, v12, v13, vcc
	v_cmp_class_f32_e32 vcc, v11, v231
	s_nop 1
	v_cndmask_b32_e32 v11, v12, v11, vcc
	v_div_scale_f32 v12, s[6:7], v11, v11, 1.0
	v_rcp_f32_e32 v13, v12
	s_nop 0
	v_fma_f32 v14, -v12, v13, 1.0
	v_fmac_f32_e32 v13, v14, v13
	v_div_scale_f32 v14, vcc, 1.0, v11, 1.0
	v_mul_f32_e32 v15, v14, v13
	v_fma_f32 v16, -v12, v15, v14
	v_fmac_f32_e32 v15, v16, v13
	v_fma_f32 v12, -v12, v15, v14
	v_div_fmas_f32 v12, v12, v13, v15
	v_div_fixup_f32 v11, v12, v11, 1.0
	v_mov_b32_e32 v12, s5
	ds_write_b64 v12, v[10:11]
; __device__ __forceinline__ void conv_item(LAS unsigned char* lds, const bf16* PROJ, bf16* MIX, const float* cw, const float* cb, const float* lg, const float* lb, int item, int tid) {
;     ...
;     for (int q = 0; q < 4; ++q) { const int tk = 4 * wid + q; float v[8]; float s = 0.f;
; #pragma unroll
;         for (int i = 0; i < 8; ++i) { v[i] = cbuf[tk * 512 + lane + 64 * i]; s += v[i]; }
;         const float mean = wave_sum(s, lane) * (1.f / 512.f); float s2 = 0.f;
; #pragma unroll
;         for (int i = 0; i < 8; ++i) { const float d = v[i] - mean; s2 += d * d; }
;         const float rstd = 1.0f / sqrtf(wave_sum(s2, lane) * (1.f / 512.f) + 1e-5f);
;         if (lane == 0) { st[2 * tk] = mean; st[2 * tk + 1] = rstd; } }
.LBB0_434:
	s_or_b64 exec, exec, s[0:1]
	s_or_b32 s5, s4, 1
	v_lshl_add_u32 v10, s5, 11, v9
	s_waitcnt lgkmcnt(0)
	ds_read2st64_b32 v[12:13], v10 offset1:1
	ds_read2st64_b32 v[14:15], v10 offset0:2 offset1:3
	ds_read2st64_b32 v[16:17], v10 offset0:4 offset1:5
	ds_read2st64_b32 v[18:19], v10 offset0:6 offset1:7
	s_waitcnt lgkmcnt(3)
	v_add_f32_e32 v10, 0, v12
	v_add_f32_e32 v10, v10, v13
	s_waitcnt lgkmcnt(2)
	v_add_f32_e32 v10, v10, v14
	v_add_f32_e32 v10, v10, v15
	s_waitcnt lgkmcnt(1)
	v_add_f32_e32 v10, v10, v16
	v_add_f32_e32 v10, v10, v17
	s_waitcnt lgkmcnt(0)
	v_add_f32_e32 v10, v10, v18
	v_add_f32_e32 v10, v10, v19
	s_nop 1
	v_add_f32_dpp v10, v10, v10 quad_perm:[1,0,3,2] row_mask:0xf bank_mask:0xf
	s_nop 1
	v_add_f32_dpp v10, v10, v10 quad_perm:[2,3,0,1] row_mask:0xf bank_mask:0xf
	s_nop 1
	v_add_f32_dpp v10, v10, v10 row_half_mirror row_mask:0xf bank_mask:0xf
	s_nop 1
	v_add_f32_dpp v10, v10, v10 row_mirror row_mask:0xf bank_mask:0xf
	ds_bpermute_b32 v11, v4, v10
	s_waitcnt lgkmcnt(0)
	v_add_f32_e32 v10, v10, v11
	ds_bpermute_b32 v11, v0, v10
	s_waitcnt lgkmcnt(0)
	v_add_f32_e32 v10, v10, v11
	v_fmac_f32_e32 v13, 0xbb000000, v10
	v_fmamk_f32 v11, v10, 0xbb000000, v12
	v_mul_f32_e32 v13, v13, v13
	v_fmamk_f32 v12, v10, 0xbb000000, v14
	v_fmac_f32_e32 v13, v11, v11
	v_fmac_f32_e32 v15, 0xbb000000, v10
	v_fmac_f32_e32 v13, v12, v12
	v_fmamk_f32 v14, v10, 0xbb000000, v16
	v_fmac_f32_e32 v13, v15, v15
	v_fmac_f32_e32 v17, 0xbb000000, v10
	v_fmac_f32_e32 v13, v14, v14
	v_fmamk_f32 v16, v10, 0xbb000000, v18
	v_fmac_f32_e32 v13, v17, v17
	v_fmac_f32_e32 v13, v16, v16
	v_fmac_f32_e32 v19, 0xbb000000, v10
	v_fmac_f32_e32 v13, v19, v19
	s_nop 1
	v_add_f32_dpp v11, v13, v13 quad_perm:[1,0,3,2] row_mask:0xf bank_mask:0xf
	s_nop 1
	v_add_f32_dpp v11, v11, v11 quad_perm:[2,3,0,1] row_mask:0xf bank_mask:0xf
	s_nop 1
	v_add_f32_dpp v11, v11, v11 row_half_mirror row_mask:0xf bank_mask:0xf
	s_nop 1
	v_add_f32_dpp v11, v11, v11 row_mirror row_mask:0xf bank_mask:0xf
	ds_bpermute_b32 v12, v4, v11
	s_waitcnt lgkmcnt(0)
	v_add_f32_e32 v11, v11, v12
	ds_bpermute_b32 v12, v0, v11
	s_and_saveexec_b64 s[0:1], s[8:9]
	v_readlane_b32 s18, v255, 32
	v_readlane_b32 s19, v255, 33
	s_cbranch_execz .LBB0_436
	s_waitcnt lgkmcnt(0)
	v_add_f32_e32 v11, v11, v12
	v_fmamk_f32 v11, v11, 0x3b000000, v232
	v_mul_f32_e32 v12, 0x4f800000, v11
	v_cmp_gt_f32_e32 vcc, s80, v11
	s_lshl_b32 s5, s5, 3
	s_add_i32 s5, s5, 0
	v_cndmask_b32_e32 v11, v11, v12, vcc
	v_sqrt_f32_e32 v12, v11
	s_add_i32 s5, s5, 0x10000
	v_mul_f32_e32 v10, 0x3b000000, v10
	v_add_u32_e32 v13, -1, v12
	v_fma_f32 v15, -v13, v12, v11
	v_add_u32_e32 v14, 1, v12
	v_cmp_ge_f32_e64 s[10:11], 0, v15
	s_nop 1
	v_cndmask_b32_e64 v13, v12, v13, s[10:11]
	v_fma_f32 v12, -v14, v12, v11
	v_cmp_lt_f32_e64 s[10:11], 0, v12
	s_nop 1
	v_cndmask_b32_e64 v12, v13, v14, s[10:11]
	v_mul_f32_e32 v13, 0x37800000, v12
	v_cndmask_b32_e32 v12, v12, v13, vcc
	v_cmp_class_f32_e32 vcc, v11, v231
	s_nop 1
	v_cndmask_b32_e32 v11, v12, v11, vcc
	v_div_scale_f32 v12, s[6:7], v11, v11, 1.0
	v_rcp_f32_e32 v13, v12
	s_nop 0
	v_fma_f32 v14, -v12, v13, 1.0
	v_fmac_f32_e32 v13, v14, v13
	v_div_scale_f32 v14, vcc, 1.0, v11, 1.0
	v_mul_f32_e32 v15, v14, v13
	v_fma_f32 v16, -v12, v15, v14
	v_fmac_f32_e32 v15, v16, v13
	v_fma_f32 v12, -v12, v15, v14
	v_div_fmas_f32 v12, v12, v13, v15
	v_div_fixup_f32 v11, v12, v11, 1.0
	v_mov_b32_e32 v12, s5
	ds_write_b64 v12, v[10:11]
; __device__ __forceinline__ void conv_item(LAS unsigned char* lds, const bf16* PROJ, bf16* MIX, const float* cw, const float* cb, const float* lg, const float* lb, int item, int tid) {
;     ...
;     for (int q = 0; q < 4; ++q) { const int tk = 4 * wid + q; float v[8]; float s = 0.f;
; #pragma unroll
;         for (int i = 0; i < 8; ++i) { v[i] = cbuf[tk * 512 + lane + 64 * i]; s += v[i]; }
;         const float mean = wave_sum(s, lane) * (1.f / 512.f); float s2 = 0.f;
; #pragma unroll
;         for (int i = 0; i < 8; ++i) { const float d = v[i] - mean; s2 += d * d; }
;         const float rstd = 1.0f / sqrtf(wave_sum(s2, lane) * (1.f / 512.f) + 1e-5f);
;         if (lane == 0) { st[2 * tk] = mean; st[2 * tk + 1] = rstd; } }
.LBB0_436:
	s_or_b64 exec, exec, s[0:1]
	s_or_b32 s4, s4, 2
	v_lshl_add_u32 v10, s4, 11, v9
	s_waitcnt lgkmcnt(0)
	ds_read2st64_b32 v[12:13], v10 offset1:1
	ds_read2st64_b32 v[14:15], v10 offset0:2 offset1:3
	ds_read2st64_b32 v[16:17], v10 offset0:4 offset1:5
	ds_read2st64_b32 v[18:19], v10 offset0:6 offset1:7
	s_waitcnt lgkmcnt(3)
	v_add_f32_e32 v10, 0, v12
	v_add_f32_e32 v10, v10, v13
	s_waitcnt lgkmcnt(2)
	v_add_f32_e32 v10, v10, v14
	v_add_f32_e32 v10, v10, v15
	s_waitcnt lgkmcnt(1)
	v_add_f32_e32 v10, v10, v16
	v_add_f32_e32 v10, v10, v17
	s_waitcnt lgkmcnt(0)
	v_add_f32_e32 v10, v10, v18
	v_add_f32_e32 v10, v10, v19
	s_nop 1
	v_add_f32_dpp v10, v10, v10 quad_perm:[1,0,3,2] row_mask:0xf bank_mask:0xf
	s_nop 1
	v_add_f32_dpp v10, v10, v10 quad_perm:[2,3,0,1] row_mask:0xf bank_mask:0xf
	s_nop 1
	v_add_f32_dpp v10, v10, v10 row_half_mirror row_mask:0xf bank_mask:0xf
	s_nop 1
	v_add_f32_dpp v10, v10, v10 row_mirror row_mask:0xf bank_mask:0xf
	ds_bpermute_b32 v11, v4, v10
	s_waitcnt lgkmcnt(0)
	v_add_f32_e32 v10, v10, v11
	ds_bpermute_b32 v11, v0, v10
	s_waitcnt lgkmcnt(0)
	v_add_f32_e32 v10, v10, v11
	v_fmac_f32_e32 v13, 0xbb000000, v10
	v_fmamk_f32 v11, v10, 0xbb000000, v12
	v_mul_f32_e32 v13, v13, v13
	v_fmamk_f32 v12, v10, 0xbb000000, v14
	v_fmac_f32_e32 v13, v11, v11
	v_fmac_f32_e32 v15, 0xbb000000, v10
	v_fmac_f32_e32 v13, v12, v12
	v_fmamk_f32 v14, v10, 0xbb000000, v16
	v_fmac_f32_e32 v13, v15, v15
	v_fmac_f32_e32 v17, 0xbb000000, v10
	v_fmac_f32_e32 v13, v14, v14
	v_fmamk_f32 v16, v10, 0xbb000000, v18
	v_fmac_f32_e32 v13, v17, v17
	v_fmac_f32_e32 v13, v16, v16
	v_fmac_f32_e32 v19, 0xbb000000, v10
	v_fmac_f32_e32 v13, v19, v19
	s_nop 1
	v_add_f32_dpp v11, v13, v13 quad_perm:[1,0,3,2] row_mask:0xf bank_mask:0xf
	s_nop 1
	v_add_f32_dpp v11, v11, v11 quad_perm:[2,3,0,1] row_mask:0xf bank_mask:0xf
	s_nop 1
	v_add_f32_dpp v11, v11, v11 row_half_mirror row_mask:0xf bank_mask:0xf
	s_nop 1
	v_add_f32_dpp v11, v11, v11 row_mirror row_mask:0xf bank_mask:0xf
	ds_bpermute_b32 v12, v4, v11
	s_waitcnt lgkmcnt(0)
	v_add_f32_e32 v11, v11, v12
	ds_bpermute_b32 v12, v0, v11
	s_and_saveexec_b64 s[0:1], s[8:9]
	s_cbranch_execz .LBB0_438
	s_waitcnt lgkmcnt(0)
	v_add_f32_e32 v11, v11, v12
	v_fmamk_f32 v11, v11, 0x3b000000, v232
	v_mul_f32_e32 v12, 0x4f800000, v11
	v_cmp_gt_f32_e32 vcc, s80, v11
	s_lshl_b32 s4, s4, 3
	s_add_i32 s4, s4, 0
	v_cndmask_b32_e32 v11, v11, v12, vcc
	v_sqrt_f32_e32 v12, v11
	s_add_i32 s4, s4, 0x10000
	v_mul_f32_e32 v10, 0x3b000000, v10
	v_add_u32_e32 v13, -1, v12
	v_fma_f32 v15, -v13, v12, v11
	v_add_u32_e32 v14, 1, v12
	v_cmp_ge_f32_e64 s[10:11], 0, v15
	s_nop 1
	v_cndmask_b32_e64 v13, v12, v13, s[10:11]
	v_fma_f32 v12, -v14, v12, v11
	v_cmp_lt_f32_e64 s[10:11], 0, v12
	s_nop 1
	v_cndmask_b32_e64 v12, v13, v14, s[10:11]
	v_mul_f32_e32 v13, 0x37800000, v12
	v_cndmask_b32_e32 v12, v12, v13, vcc
	v_cmp_class_f32_e32 vcc, v11, v231
	s_nop 1
	v_cndmask_b32_e32 v11, v12, v11, vcc
	v_div_scale_f32 v12, s[6:7], v11, v11, 1.0
	v_rcp_f32_e32 v13, v12
	s_nop 0
	v_fma_f32 v14, -v12, v13, 1.0
	v_fmac_f32_e32 v13, v14, v13
	v_div_scale_f32 v14, vcc, 1.0, v11, 1.0
	v_mul_f32_e32 v15, v14, v13
	v_fma_f32 v16, -v12, v15, v14
	v_fmac_f32_e32 v15, v16, v13
	v_fma_f32 v12, -v12, v15, v14
	v_div_fmas_f32 v12, v12, v13, v15
	v_div_fixup_f32 v11, v12, v11, 1.0
	v_mov_b32_e32 v12, s4
	ds_write_b64 v12, v[10:11]
.LBB0_438:
	s_or_b64 exec, exec, s[0:1]
	s_or_b32 s3, s3, 3
	v_lshl_add_u32 v9, s3, 11, v9
	ds_read2st64_b32 v[10:11], v9 offset1:1
	s_waitcnt lgkmcnt(1)
	ds_read2st64_b32 v[12:13], v9 offset0:2 offset1:3
	ds_read2st64_b32 v[14:15], v9 offset0:4 offset1:5
	ds_read2st64_b32 v[16:17], v9 offset0:6 offset1:7
	s_waitcnt lgkmcnt(3)
	v_add_f32_e32 v9, 0, v10
	v_add_f32_e32 v9, v9, v11
	s_waitcnt lgkmcnt(2)
	v_add_f32_e32 v9, v9, v12
	v_add_f32_e32 v9, v9, v13
	s_waitcnt lgkmcnt(1)
	v_add_f32_e32 v9, v9, v14
	v_add_f32_e32 v9, v9, v15
	s_waitcnt lgkmcnt(0)
	v_add_f32_e32 v9, v9, v16
	v_add_f32_e32 v9, v9, v17
	s_nop 1
	v_add_f32_dpp v9, v9, v9 quad_perm:[1,0,3,2] row_mask:0xf bank_mask:0xf
	s_nop 1
	v_add_f32_dpp v9, v9, v9 quad_perm:[2,3,0,1] row_mask:0xf bank_mask:0xf
	s_nop 1
	v_add_f32_dpp v9, v9, v9 row_half_mirror row_mask:0xf bank_mask:0xf
	s_nop 1
	v_add_f32_dpp v9, v9, v9 row_mirror row_mask:0xf bank_mask:0xf
	ds_bpermute_b32 v18, v4, v9
	s_waitcnt lgkmcnt(0)
	v_add_f32_e32 v9, v9, v18
	ds_bpermute_b32 v18, v0, v9
	s_waitcnt lgkmcnt(0)
	v_add_f32_e32 v9, v9, v18
	v_fmac_f32_e32 v11, 0xbb000000, v9
	v_fmamk_f32 v10, v9, 0xbb000000, v10
	v_mul_f32_e32 v11, v11, v11
	v_fmamk_f32 v12, v9, 0xbb000000, v12
	v_fmac_f32_e32 v11, v10, v10
	v_fmac_f32_e32 v13, 0xbb000000, v9
	v_fmac_f32_e32 v11, v12, v12
	v_fmamk_f32 v14, v9, 0xbb000000, v14
	v_fmac_f32_e32 v11, v13, v13
	v_fmac_f32_e32 v15, 0xbb000000, v9
	v_fmac_f32_e32 v11, v14, v14
	v_fmamk_f32 v16, v9, 0xbb000000, v16
	v_fmac_f32_e32 v11, v15, v15
	v_fmac_f32_e32 v11, v16, v16
	v_fmac_f32_e32 v17, 0xbb000000, v9
	v_fmac_f32_e32 v11, v17, v17
	s_nop 1
	v_add_f32_dpp v8, v11, v11 quad_perm:[1,0,3,2] row_mask:0xf bank_mask:0xf
	s_nop 1
	v_add_f32_dpp v7, v8, v8 quad_perm:[2,3,0,1] row_mask:0xf bank_mask:0xf
	s_nop 1
	v_add_f32_dpp v6, v7, v7 row_half_mirror row_mask:0xf bank_mask:0xf
	s_nop 1
	v_add_f32_dpp v5, v6, v6 row_mirror row_mask:0xf bank_mask:0xf
	ds_bpermute_b32 v4, v4, v5
	s_waitcnt lgkmcnt(0)
	v_add_f32_e32 v4, v5, v4
	ds_bpermute_b32 v0, v0, v4
	s_and_saveexec_b64 s[0:1], s[8:9]
	s_cbranch_execz .LBB0_440
	s_waitcnt lgkmcnt(0)
	v_add_f32_e32 v0, v4, v0
	v_fmamk_f32 v0, v0, 0x3b000000, v232
	v_mul_f32_e32 v4, 0x4f800000, v0
	v_cmp_gt_f32_e32 vcc, s80, v0
	s_lshl_b32 s3, s3, 3
	s_add_i32 s3, s3, 0
	v_cndmask_b32_e32 v0, v0, v4, vcc
	v_sqrt_f32_e32 v4, v0
	s_add_i32 s3, s3, 0x10000
	v_add_u32_e32 v5, -1, v4
	v_fma_f32 v7, -v5, v4, v0
	v_add_u32_e32 v6, 1, v4
	v_cmp_ge_f32_e64 s[8:9], 0, v7
	s_nop 1
	v_cndmask_b32_e64 v5, v4, v5, s[8:9]
	v_fma_f32 v4, -v6, v4, v0
	v_cmp_lt_f32_e64 s[8:9], 0, v4
	s_nop 1
	v_cndmask_b32_e64 v4, v5, v6, s[8:9]
	v_mul_f32_e32 v5, 0x37800000, v4
	v_cndmask_b32_e32 v4, v4, v5, vcc
	v_cmp_class_f32_e32 vcc, v0, v231
	s_nop 1
	v_cndmask_b32_e32 v0, v4, v0, vcc
	v_div_scale_f32 v5, s[4:5], v0, v0, 1.0
	v_rcp_f32_e32 v6, v5
	v_mul_f32_e32 v4, 0x3b000000, v9
	v_fma_f32 v7, -v5, v6, 1.0
	v_fmac_f32_e32 v6, v7, v6
	v_div_scale_f32 v7, vcc, 1.0, v0, 1.0
	v_mul_f32_e32 v8, v7, v6
	v_fma_f32 v9, -v5, v8, v7
	v_fmac_f32_e32 v8, v9, v6
	v_fma_f32 v5, -v5, v8, v7
	v_div_fmas_f32 v5, v5, v6, v8
	v_div_fixup_f32 v5, v5, v0, 1.0
	v_mov_b32_e32 v0, s3
	ds_write_b64 v0, v[4:5]

; __device__ __forceinline__ unsigned cvtpk(float lo, float hi) { f32x2_t v = {lo, hi}; bf16x2_t b = __builtin_convertvector(v, bf16x2_t); return __builtin_bit_cast(unsigned, b); }
; __device__ __forceinline__ void row_pass(const float* xsrc, float* xdst, const bf16* F, float coef, const float* g_post, const float* g_pre, bf16* XN, int gw, int NGW, int lane) {
;     ...
;         u32x2* xo = (u32x2*)((bf16*)xdst + (size_t)m * D) + lane;
; #pragma unroll
;         for (int j = 0; j < 4; ++j) { u32x2 w; w.x = cvtpk(v[j].x, v[j].y); w.y = cvtpk(v[j].z, v[j].w); xo[64 * j] = w; }
;         if (XN) {
;             float ss = 0.f;
; #pragma unroll
;             for (int j = 0; j < 4; ++j) ss += (v[j].x * v[j].x + v[j].y * v[j].y) + (v[j].z * v[j].z + v[j].w * v[j].w);
;             const float rs = 1.0f / sqrtf(wave_sum(ss, lane) * (1.f / D) + 1e-6f);
;             u32x2* o8 = (u32x2*)(XN + (size_t)m * D) + lane;
; #pragma unroll
;             for (int j = 0; j < 4; ++j) { const f32x4 g = ((const f32x4*)g_pre)[lane + 64 * j]; const f32x4 y = v[j] * g * rs; u32x2 w; w.x = cvtpk(y.x, y.y); w.y = cvtpk(y.z, y.w); o8[64 * j] = w; }
;         }
.Lrp_nopf:
	v_cvt_pk_bf16_f32 v30, v18, v19
	v_cvt_pk_bf16_f32 v31, v20, v21
	v_cvt_pk_bf16_f32 v32, v22, v23
	v_cvt_pk_bf16_f32 v33, v24, v25
	v_pk_mul_f32 v[40:41], v[20:21], v[20:21]
	v_pk_mul_f32 v[42:43], v[18:19], v[18:19]
	v_pk_mul_f32 v[44:45], v[24:25], v[24:25]
	v_pk_mul_f32 v[46:47], v[22:23], v[22:23]
	v_cvt_pk_bf16_f32 v36, v26, v27
	v_cvt_pk_bf16_f32 v37, v28, v29
	v_cvt_pk_bf16_f32 v38, v2, v3
	v_cvt_pk_bf16_f32 v39, v4, v5
	global_store_dwordx2 v[8:9], v[30:31], off offset:-1536
	global_store_dwordx2 v[8:9], v[32:33], off offset:-1024
	global_store_dwordx2 v[8:9], v[36:37], off offset:-512
	global_store_dwordx2 v[8:9], v[38:39], off
	v_pk_mov_b32 v[30:31], v[42:43], v[40:41] op_sel:[1,0]
	v_mov_b32_e32 v43, v41
	v_pk_mov_b32 v[32:33], v[46:47], v[44:45] op_sel:[1,0]
	v_mov_b32_e32 v47, v45
	v_pk_add_f32 v[40:41], v[30:31], v[42:43]
	v_pk_add_f32 v[42:43], v[32:33], v[46:47]
	v_mul_f32_e32 v49, v2, v2
	v_mul_f32_e32 v0, v27, v27
	v_mul_f32_e32 v48, v29, v29
	v_mul_f32_e32 v50, v3, v3
	v_mul_f32_e32 v51, v4, v4
	v_mul_f32_e32 v52, v5, v5
	v_pk_fma_f32 v[36:37], v[26:27], v[26:27], v[0:1] op_sel_hi:[1,1,0]
	v_pk_fma_f32 v[38:39], v[28:29], v[28:29], v[48:49] op_sel_hi:[1,1,0]
	v_pk_add_f32 v[40:41], v[40:41], v[40:41] op_sel:[0,1] op_sel_hi:[1,0]
	v_pk_add_f32 v[42:43], v[42:43], v[42:43] op_sel:[0,1] op_sel_hi:[1,0]
	v_mov_b32_e32 v37, v51
	v_mov_b32_e32 v39, v52
	v_mov_b32_e32 v41, v49
	v_mov_b32_e32 v43, v50
	v_pk_add_f32 v[36:37], v[36:37], v[38:39]
	v_pk_add_f32 v[38:39], v[40:41], v[42:43]
	v_lshl_add_u64 v[8:9], v[8:9], 0, s[2:3]
	v_pk_add_f32 v[36:37], v[38:39], v[36:37]
	v_pk_mul_f32 v[20:21], v[20:21], v[62:63]
	v_add_f32_e32 v0, v36, v37
	v_pk_mul_f32 v[18:19], v[18:19], v[60:61]
	s_nop 1
	v_add_f32_dpp v0, v0, v0 quad_perm:[1,0,3,2] row_mask:0xf bank_mask:0xf
	s_nop 1
	v_add_f32_dpp v0, v0, v0 quad_perm:[2,3,0,1] row_mask:0xf bank_mask:0xf
	s_nop 1
	v_add_f32_dpp v0, v0, v0 row_half_mirror row_mask:0xf bank_mask:0xf
	s_nop 1
	v_add_f32_dpp v0, v0, v0 row_mirror row_mask:0xf bank_mask:0xf
	ds_bpermute_b32 v36, v16, v0
	s_waitcnt lgkmcnt(0)
	v_add_f32_e32 v0, v0, v36
	ds_bpermute_b32 v36, v17, v0
	s_waitcnt lgkmcnt(0)
	v_add_f32_e32 v0, v0, v36
	v_fmamk_f32 v0, v0, 0x3a800000, v230
	v_mul_f32_e32 v36, 0x4f800000, v0
	v_cmp_gt_f32_e32 vcc, s80, v0
	s_nop 1
	v_cndmask_b32_e32 v0, v0, v36, vcc
	v_sqrt_f32_e32 v36, v0
	s_nop 0
	v_add_u32_e32 v37, -1, v36
	v_add_u32_e32 v38, 1, v36
	v_fma_f32 v39, -v37, v36, v0
	v_fma_f32 v40, -v38, v36, v0
	v_cmp_ge_f32_e64 s[6:7], 0, v39
	s_nop 1
	v_cndmask_b32_e64 v36, v36, v37, s[6:7]
	v_cmp_lt_f32_e64 s[6:7], 0, v40
	s_nop 1
	v_cndmask_b32_e64 v36, v36, v38, s[6:7]
	v_mul_f32_e32 v37, 0x37800000, v36
	v_cndmask_b32_e32 v36, v36, v37, vcc
	v_cmp_class_f32_e32 vcc, v0, v231
	s_nop 1
	v_cndmask_b32_e32 v0, v36, v0, vcc
	v_div_scale_f32 v36, s[6:7], v0, v0, 1.0
	v_rcp_f32_e32 v38, v36
	v_div_scale_f32 v37, vcc, 1.0, v0, 1.0
	v_fma_f32 v39, -v36, v38, 1.0
	v_fmac_f32_e32 v38, v39, v38
	v_mul_f32_e32 v39, v37, v38
	v_fma_f32 v40, -v36, v39, v37
	v_fmac_f32_e32 v39, v40, v38
	v_fma_f32 v36, -v36, v39, v37
	v_div_fmas_f32 v36, v36, v38, v39
	v_div_fixup_f32 v0, v36, v0, 1.0
	v_pk_mul_f32 v[20:21], v[20:21], v[0:1] op_sel_hi:[1,0]
	v_pk_mul_f32 v[18:19], v[18:19], v[0:1] op_sel_hi:[1,0]
	s_nop 0
	v_cvt_pk_bf16_f32 v18, v18, v19
	v_cvt_pk_bf16_f32 v19, v20, v21
	global_store_dwordx2 v[34:35], v[18:19], off offset:-1536
	v_pk_mul_f32 v[20:21], v[24:25], v[66:67]
	v_pk_mul_f32 v[18:19], v[22:23], v[64:65]
	v_pk_mul_f32 v[20:21], v[20:21], v[0:1] op_sel_hi:[1,0]
	v_pk_mul_f32 v[18:19], v[18:19], v[0:1] op_sel_hi:[1,0]
	s_nop 0
	v_cvt_pk_bf16_f32 v18, v18, v19
	v_cvt_pk_bf16_f32 v19, v20, v21
	global_store_dwordx2 v[34:35], v[18:19], off offset:-1024
	v_pk_mul_f32 v[20:21], v[28:29], v[70:71]
	v_pk_mul_f32 v[18:19], v[26:27], v[68:69]
	v_pk_mul_f32 v[20:21], v[20:21], v[0:1] op_sel_hi:[1,0]
	v_pk_mul_f32 v[18:19], v[18:19], v[0:1] op_sel_hi:[1,0]
	s_nop 0
	v_cvt_pk_bf16_f32 v18, v18, v19
	v_cvt_pk_bf16_f32 v19, v20, v21
	global_store_dwordx2 v[34:35], v[18:19], off offset:-512
	v_pk_mul_f32 v[4:5], v[4:5], v[74:75]
	v_pk_mul_f32 v[2:3], v[2:3], v[72:73]
	v_pk_mul_f32 v[4:5], v[0:1], v[4:5] op_sel_hi:[0,1]
	v_pk_mul_f32 v[2:3], v[0:1], v[2:3] op_sel_hi:[0,1]
	v_cvt_pk_bf16_f32 v2, v2, v3
	v_cvt_pk_bf16_f32 v3, v4, v5
	global_store_dwordx2 v[34:35], v[2:3], off
	s_cbranch_scc1 .LBB0_518
	s_branch .LBB0_7
